# k9: attention loop rewrite (LDS prefetch hoist, next-tile row max in MFMA shadow, C-init fold of running max, staging in PV section), wide-store attention epilogue via LDS transpose, prologue store dr
# speedup vs baseline: 1.0108x; 1.0108x over previous
; __device__ __forceinline__ unsigned cvtpk(float lo, float hi) { f32x2_t v = {lo, hi}; bf16x2_t b = __builtin_convertvector(v, bf16x2_t); return __builtin_bit_cast(unsigned, b); }
; __device__ __forceinline__ int crow(int r, int hi) { return (r & 3) + 8 * (r >> 2) + 4 * hi; }
; __device__ __forceinline__ void attn_unit(const Ctx& c, int bh, int qb, const bf16_t* Q, const bf16_t* Kb, const bf16_t* Vb, bf16_t* O) {
;     ...
;     lsum += __int_as_float(__builtin_amdgcn_ds_bpermute((lane ^ 32) * 4, __float_as_int(lsum)));
;     if (hi == 0) wsf[r32] = 1.0f / lsum;
;     asm volatile("" ::: "memory");
;     bf16_t* op = O + (rowbase + q0 + wid * 32) * 1024 + h * 64 + r32;
; #pragma unroll
;     for (int r = 0; r < 16; ++r) { const int qq = crow(r, hi); const float rl = wsf[qq];
;         op[(size_t)qq * 1024] = (bf16_t)(cvtpk(o[0][r] * rl, 0.f) & 0xffffu); op[(size_t)qq * 1024 + 32] = (bf16_t)(cvtpk(o[1][r] * rl, 0.f) & 0xffffu); }
;     asm volatile("" ::: "memory");
.LBB0_276:
	s_or_b64 exec, exec, s[6:7]
	s_lshl_b64 s[6:7], s[46:47], 11
	s_waitcnt lgkmcnt(0)
	ds_read_b128 v[32:35], v221
	ds_read_b128 v[36:39], v221 offset:32
	ds_read_b128 v[40:43], v221 offset:64
	ds_read_b128 v[44:47], v221 offset:96
	s_add_u32 s5, s76, s6
	s_addc_u32 s6, s77, s7
	s_lshl_b32 s4, s4, 1
	s_add_u32 s4, s5, s4
	s_addc_u32 s5, s6, 0
	v_readlane_b32 s8, v254, 61
	s_mul_i32 s8, s8, 0x48
	s_add_i32 s8, s8, 0x14000
	s_mov_b64 s[10:11], 0x4000
	v_cndmask_b32_e64 v48, 1, 0, s[44:45]
	v_lshl_add_u32 v49, v48, 5, v146
	v_mul_u32_u24_e32 v50, 0x240, v48
	v_lshl_add_u32 v50, v146, 1, v50
	v_add_u32_e32 v50, s8, v50
	v_lshrrev_b32_e32 v51, 3, v49
	v_and_b32_e32 v52, 7, v49
	v_mul_u32_u24_e32 v53, 0x90, v51
	v_lshl_add_u32 v53, v52, 4, v53
	v_add_u32_e32 v53, s8, v53
	v_lshlrev_b32_e32 v54, 11, v51
	v_lshl_add_u32 v54, v52, 4, v54
	v_mov_b32_e32 v55, 0
	v_lshl_add_u64 v[54:55], s[4:5], 0, v[54:55]
	s_waitcnt lgkmcnt(0)
	v_mul_f32_e32 v56, v16, v32
	v_mul_f32_e32 v57, v0, v32
	v_cvt_pk_bf16_f32 v56, v56, v57
	ds_write_b16 v50, v56
	ds_write_b16_d16_hi v50, v56 offset:64
	v_mul_f32_e32 v58, v17, v33
	v_mul_f32_e32 v59, v1, v33
	v_cvt_pk_bf16_f32 v58, v58, v59
	ds_write_b16 v50, v58 offset:144
	ds_write_b16_d16_hi v50, v58 offset:208
	v_mul_f32_e32 v56, v18, v34
	v_mul_f32_e32 v57, v2, v34
	v_cvt_pk_bf16_f32 v56, v56, v57
	ds_write_b16 v50, v56 offset:288
	ds_write_b16_d16_hi v50, v56 offset:352
	v_mul_f32_e32 v58, v19, v35
	v_mul_f32_e32 v59, v3, v35
	v_cvt_pk_bf16_f32 v58, v58, v59
	ds_write_b16 v50, v58 offset:432
	ds_write_b16_d16_hi v50, v58 offset:496
	v_mul_f32_e32 v56, v20, v36
	v_mul_f32_e32 v57, v4, v36
	v_cvt_pk_bf16_f32 v56, v56, v57
	ds_write_b16 v50, v56 offset:1152
	ds_write_b16_d16_hi v50, v56 offset:1216
	v_mul_f32_e32 v58, v21, v37
	v_mul_f32_e32 v59, v5, v37
	v_cvt_pk_bf16_f32 v58, v58, v59
	ds_write_b16 v50, v58 offset:1296
	ds_write_b16_d16_hi v50, v58 offset:1360
	v_mul_f32_e32 v56, v22, v38
	v_mul_f32_e32 v57, v6, v38
	v_cvt_pk_bf16_f32 v56, v56, v57
	ds_write_b16 v50, v56 offset:1440
	ds_write_b16_d16_hi v50, v56 offset:1504
	v_mul_f32_e32 v58, v23, v39
	v_mul_f32_e32 v59, v7, v39
	v_cvt_pk_bf16_f32 v58, v58, v59
	ds_write_b16 v50, v58 offset:1584
	ds_write_b16_d16_hi v50, v58 offset:1648
	v_mul_f32_e32 v56, v24, v40
	v_mul_f32_e32 v57, v8, v40
	v_cvt_pk_bf16_f32 v56, v56, v57
	ds_write_b16 v50, v56 offset:2304
	ds_write_b16_d16_hi v50, v56 offset:2368
	v_mul_f32_e32 v58, v25, v41
	v_mul_f32_e32 v59, v9, v41
	v_cvt_pk_bf16_f32 v58, v58, v59
	ds_write_b16 v50, v58 offset:2448
	ds_write_b16_d16_hi v50, v58 offset:2512
	v_mul_f32_e32 v56, v26, v42
	v_mul_f32_e32 v57, v10, v42
	v_cvt_pk_bf16_f32 v56, v56, v57
	ds_write_b16 v50, v56 offset:2592
	ds_write_b16_d16_hi v50, v56 offset:2656
	v_mul_f32_e32 v58, v27, v43
	v_mul_f32_e32 v59, v11, v43
	v_cvt_pk_bf16_f32 v58, v58, v59
	ds_write_b16 v50, v58 offset:2736
	ds_write_b16_d16_hi v50, v58 offset:2800
	v_mul_f32_e32 v56, v28, v44
	v_mul_f32_e32 v57, v12, v44
	v_cvt_pk_bf16_f32 v56, v56, v57
	ds_write_b16 v50, v56 offset:3456
	ds_write_b16_d16_hi v50, v56 offset:3520
	v_mul_f32_e32 v58, v29, v45
	v_mul_f32_e32 v59, v13, v45
	v_cvt_pk_bf16_f32 v58, v58, v59
	ds_write_b16 v50, v58 offset:3600
	ds_write_b16_d16_hi v50, v58 offset:3664
	v_mul_f32_e32 v56, v30, v46
	v_mul_f32_e32 v57, v14, v46
	v_cvt_pk_bf16_f32 v56, v56, v57
	ds_write_b16 v50, v56 offset:3744
	ds_write_b16_d16_hi v50, v56 offset:3808
	v_mul_f32_e32 v58, v31, v47
	v_mul_f32_e32 v59, v15, v47
	v_cvt_pk_bf16_f32 v58, v58, v59
	ds_write_b16 v50, v58 offset:3888
	ds_write_b16_d16_hi v50, v58 offset:3952
	s_waitcnt lgkmcnt(0)
	ds_read_b128 v[56:59], v53
	ds_read_b128 v[60:63], v53 offset:1152
	ds_read_b128 v[64:67], v53 offset:2304
	ds_read_b128 v[68:71], v53 offset:3456
	v_lshl_add_u64 v[72:73], v[54:55], 0, s[10:11]
	v_lshl_add_u64 v[74:75], v[72:73], 0, s[10:11]
	v_lshl_add_u64 v[76:77], v[74:75], 0, s[10:11]
	s_waitcnt lgkmcnt(3)
	global_store_dwordx4 v[54:55], v[56:59], off
	s_waitcnt lgkmcnt(2)
	global_store_dwordx4 v[72:73], v[60:63], off
	s_waitcnt lgkmcnt(1)
	global_store_dwordx4 v[74:75], v[64:67], off
	s_waitcnt lgkmcnt(0)
	global_store_dwordx4 v[76:77], v[68:71], off
	s_add_i32 s3, s3, s15
	s_cmpk_gt_i32 s3, 0x3ff
	s_cbranch_scc1 .LBB0_314

; __device__ __forceinline__ unsigned cvtpk(float lo, float hi) { f32x2_t v = {lo, hi}; bf16x2_t b = __builtin_convertvector(v, bf16x2_t); return __builtin_bit_cast(unsigned, b); }
;     __device__ __forceinline__ void operator()(const f32x4 (&acc)[2][2][4][2], const Unit& u, int wr, int wc, int fr, int fq, const float (&pre)[8]) const {
;         const int row0 = u.pm * BM + wr * 64 + fr; const int col0 = u.pn * 128 + wc * 32 + 8 * fq;
; #pragma unroll
;         for (int ai = 0; ai < 2; ++ai)
; #pragma unroll
;             for (int m = 0; m < 4; ++m) {
;                 bf16_t* rowp = O + (size_t)(row0 + ai * HALF + m * 16) * ldc + col0;
;                 const float rs = pre[ai * 4 + m];
;                 const f32x4 g0 = acc[ai][0][m][0] * rs, g1 = acc[ai][0][m][1] * rs, u0 = acc[ai][1][m][0] * rs, u1 = acc[ai][1][m][1] * rs;
;                 const f32x4 t0 = g0 * (-1.4426950408889634f), t1 = g1 * (-1.4426950408889634f);
;                 f32x4 e0, e1;
; #pragma unroll
;                 for (int j = 0; j < 4; ++j) { e0[j] = __builtin_amdgcn_exp2f(t0[j]); e1[j] = __builtin_amdgcn_exp2f(t1[j]); }
;                 const f32x4 d0 = e0 + 1.0f, d1 = e1 + 1.0f, p0 = g0 * u0, p1 = g1 * u1;
;                 f32x4 r0, r1;
; #pragma unroll
;                 for (int j = 0; j < 4; ++j) { r0[j] = __builtin_amdgcn_rcpf(d0[j]); r1[j] = __builtin_amdgcn_rcpf(d1[j]); }
;                 const f32x4 o0 = p0 * r0, o1 = p1 * r1;
;                 u32x4 w;
;                 w.x = cvtpk(o0[0], o0[1]); w.y = cvtpk(o0[2], o0[3]); w.z = cvtpk(o1[0], o1[1]); w.w = cvtpk(o1[2], o1[3]);
;                 *(u32x4*)rowp = w;
.LBB0_953:
	v_mov_b32_e32 v145, 0
	s_add_i32 s65, s65, s73
	v_mbcnt_lo_u32_b32 v145, -1, v145
	v_mbcnt_hi_u32_b32 v147, -1, v145
	s_lshl_b32 s6, s64, 7
	v_pk_mul_f32 v[128:129], v[154:155], v[128:129] op_sel_hi:[0,1]
	v_and_or_b32 v145, v147, 15, s65
	s_or_b32 s6, s6, s88
	v_lshrrev_b32_e32 v147, 1, v147
	v_pk_mul_f32 v[126:127], v[154:155], v[126:127] op_sel_hi:[0,1]
	v_pk_mul_f32 v[124:125], v[154:155], v[124:125] op_sel_hi:[0,1]
	v_pk_mul_f32 v[122:123], v[154:155], v[122:123] op_sel_hi:[0,1]
	v_mul_f32_e32 v155, 0xbfb8aa3b, v128
	v_and_or_b32 v158, v147, 24, s6
	v_mul_f32_e32 v147, 0xbfb8aa3b, v126
	v_exp_f32_e32 v155, v155
	v_exp_f32_e32 v147, v147
	v_mul_f32_e32 v149, 0xbfb8aa3b, v122
	v_exp_f32_e32 v149, v149
	v_mul_f32_e32 v151, 0xbfb8aa3b, v127
	v_exp_f32_e32 v151, v151
	v_mul_f32_e32 v153, 0xbfb8aa3b, v123
	v_exp_f32_e32 v153, v153
	v_mul_f32_e32 v162, 0xbfb8aa3b, v124
	v_pk_mul_f32 v[118:119], v[154:155], v[118:119] op_sel_hi:[0,1]
	v_exp_f32_e32 v165, v162
	v_mul_f32_e32 v162, 0xbfb8aa3b, v129
	v_pk_mul_f32 v[120:121], v[154:155], v[120:121] op_sel_hi:[0,1]
	v_pk_mul_f32 v[126:127], v[118:119], v[126:127]
	v_add_f32_e32 v118, 1.0, v147
	v_exp_f32_e32 v167, v162
	v_mul_f32_e32 v162, 0xbfb8aa3b, v125
	v_pk_mul_f32 v[120:121], v[120:121], v[128:129]
	v_rcp_f32_e32 v128, v118
	v_add_f32_e32 v118, 1.0, v149
	v_exp_f32_e32 v168, v162
	v_rcp_f32_e32 v162, v118
	v_add_f32_e32 v118, 1.0, v151
	v_rcp_f32_e32 v129, v118
	v_add_f32_e32 v118, 1.0, v153
	v_rcp_f32_e32 v163, v118
	v_add_f32_e32 v118, 1.0, v155
	v_rcp_f32_e32 v164, v118
	v_add_f32_e32 v118, 1.0, v165
	v_rcp_f32_e32 v166, v118
	v_add_f32_e32 v118, 1.0, v167
	v_rcp_f32_e32 v165, v118
	v_add_f32_e32 v118, 1.0, v168
	v_rcp_f32_e32 v167, v118
	v_pk_mul_f32 v[116:117], v[154:155], v[116:117] op_sel_hi:[0,1]
	v_pk_mul_f32 v[114:115], v[154:155], v[114:115] op_sel_hi:[0,1]
	v_ashrrev_i32_e32 v159, 31, v158
	v_mov_b64_e32 v[156:157], s[34:35]
	v_pk_mul_f32 v[114:115], v[114:115], v[122:123]
	v_pk_mul_f32 v[116:117], v[116:117], v[124:125]
	v_mad_i64_i32 v[160:161], s[6:7], v145, s54, v[156:157]
	v_lshlrev_b64 v[118:119], 1, v[158:159]
	v_pk_mul_f32 v[120:121], v[120:121], v[164:165]
	v_pk_mul_f32 v[122:123], v[126:127], v[128:129]
	v_pk_mul_f32 v[124:125], v[116:117], v[166:167]
	v_pk_mul_f32 v[116:117], v[114:115], v[162:163]
	v_lshl_add_u64 v[158:159], v[160:161], 0, v[118:119]
	v_cvt_pk_bf16_f32 v114, v122, v123
	v_cvt_pk_bf16_f32 v115, v120, v121
	v_cvt_pk_bf16_f32 v116, v116, v117
	v_cvt_pk_bf16_f32 v117, v124, v125
	v_pk_mul_f32 v[108:109], v[152:153], v[108:109] op_sel_hi:[0,1]
	v_pk_mul_f32 v[106:107], v[152:153], v[106:107] op_sel_hi:[0,1]
	global_store_dwordx4 v[158:159], v[114:117], off
	v_pk_mul_f32 v[112:113], v[152:153], v[112:113] op_sel_hi:[0,1]
	v_pk_mul_f32 v[110:111], v[152:153], v[110:111] op_sel_hi:[0,1]
	v_mul_f32_e32 v117, 0xbfb8aa3b, v106
	v_mul_f32_e32 v123, 0xbfb8aa3b, v108
	v_mul_f32_e32 v116, 0xbfb8aa3b, v110
	v_exp_f32_e32 v117, v117
	v_mul_f32_e32 v120, 0xbfb8aa3b, v111
	v_mul_f32_e32 v121, 0xbfb8aa3b, v107
	v_mul_f32_e32 v122, 0xbfb8aa3b, v112
	v_exp_f32_e32 v123, v123
	v_mul_f32_e32 v124, 0xbfb8aa3b, v113
	v_mul_f32_e32 v125, 0xbfb8aa3b, v109
	v_exp_f32_e32 v116, v116
	v_exp_f32_e32 v120, v120
	v_exp_f32_e32 v121, v121
	v_exp_f32_e32 v122, v122
	v_exp_f32_e32 v124, v124
	v_exp_f32_e32 v125, v125
	v_pk_mul_f32 v[102:103], v[152:153], v[102:103] op_sel_hi:[0,1]
	v_pk_mul_f32 v[104:105], v[152:153], v[104:105] op_sel_hi:[0,1]
	v_pk_mul_f32 v[102:103], v[102:103], v[110:111]
	v_add_f32_e32 v111, 1.0, v117
	v_add_f32_e32 v117, 1.0, v123
	v_pk_mul_f32 v[104:105], v[104:105], v[112:113]
	v_add_f32_e32 v110, 1.0, v116
	v_rcp_f32_e32 v112, v111
	v_add_f32_e32 v111, 1.0, v120
	v_add_f32_e32 v113, 1.0, v121
	v_add_f32_e32 v116, 1.0, v122
	v_rcp_f32_e32 v120, v117
	v_add_f32_e32 v117, 1.0, v124
	v_add_f32_e32 v121, 1.0, v125
	v_rcp_f32_e32 v110, v110
	v_rcp_f32_e32 v111, v111
	v_rcp_f32_e32 v113, v113
	v_rcp_f32_e32 v116, v116
	v_rcp_f32_e32 v117, v117
	v_rcp_f32_e32 v121, v121
	v_pk_mul_f32 v[100:101], v[152:153], v[100:101] op_sel_hi:[0,1]
	v_pk_mul_f32 v[98:99], v[152:153], v[98:99] op_sel_hi:[0,1]
	v_or_b32_e32 v114, 16, v145
	v_pk_mul_f32 v[98:99], v[98:99], v[106:107]
	v_pk_mul_f32 v[100:101], v[100:101], v[108:109]
	v_mad_i64_i32 v[114:115], s[6:7], v114, s54, v[156:157]
	v_pk_mul_f32 v[104:105], v[104:105], v[116:117]
	v_pk_mul_f32 v[102:103], v[102:103], v[110:111]
	v_pk_mul_f32 v[106:107], v[100:101], v[120:121]
	v_pk_mul_f32 v[100:101], v[98:99], v[112:113]
	v_lshl_add_u64 v[114:115], v[114:115], 0, v[118:119]
	v_cvt_pk_bf16_f32 v98, v102, v103
	v_cvt_pk_bf16_f32 v99, v104, v105
	v_cvt_pk_bf16_f32 v100, v100, v101
	v_cvt_pk_bf16_f32 v101, v106, v107
	v_pk_mul_f32 v[90:91], v[150:151], v[90:91] op_sel_hi:[0,1]
	v_pk_mul_f32 v[88:89], v[150:151], v[88:89] op_sel_hi:[0,1]
	global_store_dwordx4 v[114:115], v[98:101], off
	v_pk_mul_f32 v[94:95], v[150:151], v[94:95] op_sel_hi:[0,1]
	v_pk_mul_f32 v[92:93], v[150:151], v[92:93] op_sel_hi:[0,1]
	v_mul_f32_e32 v101, 0xbfb8aa3b, v88
	v_mul_f32_e32 v105, 0xbfb8aa3b, v90
	v_mul_f32_e32 v100, 0xbfb8aa3b, v92
	v_exp_f32_e32 v101, v101
	v_mul_f32_e32 v102, 0xbfb8aa3b, v93
	v_mul_f32_e32 v103, 0xbfb8aa3b, v89
	v_mul_f32_e32 v104, 0xbfb8aa3b, v94
	v_exp_f32_e32 v105, v105
	v_mul_f32_e32 v106, 0xbfb8aa3b, v95
	v_mul_f32_e32 v107, 0xbfb8aa3b, v91
	v_exp_f32_e32 v100, v100
	v_exp_f32_e32 v102, v102
	v_exp_f32_e32 v103, v103
	v_exp_f32_e32 v104, v104
	v_exp_f32_e32 v106, v106
	v_exp_f32_e32 v107, v107
	v_pk_mul_f32 v[84:85], v[150:151], v[84:85] op_sel_hi:[0,1]
	v_pk_mul_f32 v[86:87], v[150:151], v[86:87] op_sel_hi:[0,1]
; __device__ __forceinline__ unsigned cvtpk(float lo, float hi) { f32x2_t v = {lo, hi}; bf16x2_t b = __builtin_convertvector(v, bf16x2_t); return __builtin_bit_cast(unsigned, b); }
;     __device__ __forceinline__ void operator()(const f32x4 (&acc)[2][2][4][2], const Unit& u, int wr, int wc, int fr, int fq, const float (&pre)[8]) const {
;     ...
;         for (int ai = 0; ai < 2; ++ai)
; #pragma unroll
;             for (int m = 0; m < 4; ++m) {
;                 bf16_t* rowp = O + (size_t)(row0 + ai * HALF + m * 16) * ldc + col0;
;                 const float rs = pre[ai * 4 + m];
;                 const f32x4 g0 = acc[ai][0][m][0] * rs, g1 = acc[ai][0][m][1] * rs, u0 = acc[ai][1][m][0] * rs, u1 = acc[ai][1][m][1] * rs;
;                 const f32x4 t0 = g0 * (-1.4426950408889634f), t1 = g1 * (-1.4426950408889634f);
;                 f32x4 e0, e1;
; #pragma unroll
;                 for (int j = 0; j < 4; ++j) { e0[j] = __builtin_amdgcn_exp2f(t0[j]); e1[j] = __builtin_amdgcn_exp2f(t1[j]); }
;                 const f32x4 d0 = e0 + 1.0f, d1 = e1 + 1.0f, p0 = g0 * u0, p1 = g1 * u1;
;                 f32x4 r0, r1;
; #pragma unroll
;                 for (int j = 0; j < 4; ++j) { r0[j] = __builtin_amdgcn_rcpf(d0[j]); r1[j] = __builtin_amdgcn_rcpf(d1[j]); }
;                 const f32x4 o0 = p0 * r0, o1 = p1 * r1;
;                 u32x4 w;
;                 w.x = cvtpk(o0[0], o0[1]); w.y = cvtpk(o0[2], o0[3]); w.z = cvtpk(o1[0], o1[1]); w.w = cvtpk(o1[2], o1[3]);
;                 *(u32x4*)rowp = w;
	v_pk_mul_f32 v[84:85], v[84:85], v[92:93]
	v_add_f32_e32 v93, 1.0, v101
	v_add_f32_e32 v101, 1.0, v105
	v_pk_mul_f32 v[86:87], v[86:87], v[94:95]
	v_add_f32_e32 v92, 1.0, v100
	v_rcp_f32_e32 v94, v93
	v_add_f32_e32 v93, 1.0, v102
	v_add_f32_e32 v95, 1.0, v103
	v_add_f32_e32 v100, 1.0, v104
	v_rcp_f32_e32 v102, v101
	v_add_f32_e32 v101, 1.0, v106
	v_add_f32_e32 v103, 1.0, v107
	v_rcp_f32_e32 v92, v92
	v_rcp_f32_e32 v93, v93
	v_rcp_f32_e32 v95, v95
	v_rcp_f32_e32 v100, v100
	v_rcp_f32_e32 v101, v101
	v_rcp_f32_e32 v103, v103
	v_pk_mul_f32 v[82:83], v[150:151], v[82:83] op_sel_hi:[0,1]
	v_pk_mul_f32 v[80:81], v[150:151], v[80:81] op_sel_hi:[0,1]
	v_or_b32_e32 v98, 32, v145
	v_pk_mul_f32 v[80:81], v[80:81], v[88:89]
	v_pk_mul_f32 v[82:83], v[82:83], v[90:91]
	v_mad_i64_i32 v[98:99], s[6:7], v98, s54, v[156:157]
	v_pk_mul_f32 v[86:87], v[86:87], v[100:101]
	v_pk_mul_f32 v[84:85], v[84:85], v[92:93]
	v_pk_mul_f32 v[88:89], v[82:83], v[102:103]
	v_pk_mul_f32 v[82:83], v[80:81], v[94:95]
	v_lshl_add_u64 v[98:99], v[98:99], 0, v[118:119]
	v_cvt_pk_bf16_f32 v80, v84, v85
	v_cvt_pk_bf16_f32 v81, v86, v87
	v_cvt_pk_bf16_f32 v82, v82, v83
	v_cvt_pk_bf16_f32 v83, v88, v89
	v_pk_mul_f32 v[74:75], v[148:149], v[74:75] op_sel_hi:[0,1]
	v_pk_mul_f32 v[72:73], v[148:149], v[72:73] op_sel_hi:[0,1]
	global_store_dwordx4 v[98:99], v[80:83], off
	v_pk_mul_f32 v[78:79], v[148:149], v[78:79] op_sel_hi:[0,1]
	v_pk_mul_f32 v[76:77], v[148:149], v[76:77] op_sel_hi:[0,1]
	v_mul_f32_e32 v83, 0xbfb8aa3b, v72
	v_mul_f32_e32 v87, 0xbfb8aa3b, v74
	v_mul_f32_e32 v82, 0xbfb8aa3b, v76
	v_exp_f32_e32 v83, v83
	v_mul_f32_e32 v84, 0xbfb8aa3b, v77
	v_mul_f32_e32 v85, 0xbfb8aa3b, v73
	v_mul_f32_e32 v86, 0xbfb8aa3b, v78
	v_exp_f32_e32 v87, v87
	v_mul_f32_e32 v88, 0xbfb8aa3b, v79
	v_mul_f32_e32 v89, 0xbfb8aa3b, v75
	v_exp_f32_e32 v82, v82
	v_exp_f32_e32 v84, v84
	v_exp_f32_e32 v85, v85
	v_exp_f32_e32 v86, v86
	v_exp_f32_e32 v88, v88
	v_exp_f32_e32 v89, v89
	v_pk_mul_f32 v[68:69], v[148:149], v[68:69] op_sel_hi:[0,1]
	v_pk_mul_f32 v[70:71], v[148:149], v[70:71] op_sel_hi:[0,1]
	v_pk_mul_f32 v[68:69], v[68:69], v[76:77]
	v_add_f32_e32 v77, 1.0, v83
	v_add_f32_e32 v83, 1.0, v87
	v_pk_mul_f32 v[70:71], v[70:71], v[78:79]
	v_add_f32_e32 v76, 1.0, v82
	v_rcp_f32_e32 v78, v77
	v_add_f32_e32 v77, 1.0, v84
	v_add_f32_e32 v79, 1.0, v85
	v_add_f32_e32 v82, 1.0, v86
	v_rcp_f32_e32 v84, v83
	v_add_f32_e32 v83, 1.0, v88
	v_add_f32_e32 v85, 1.0, v89
	v_rcp_f32_e32 v76, v76
	v_rcp_f32_e32 v77, v77
	v_rcp_f32_e32 v79, v79
	v_rcp_f32_e32 v82, v82
	v_rcp_f32_e32 v83, v83
	v_rcp_f32_e32 v85, v85
	v_pk_mul_f32 v[66:67], v[148:149], v[66:67] op_sel_hi:[0,1]
	v_pk_mul_f32 v[64:65], v[148:149], v[64:65] op_sel_hi:[0,1]
	v_or_b32_e32 v80, 48, v145
	v_pk_mul_f32 v[64:65], v[64:65], v[72:73]
	v_pk_mul_f32 v[66:67], v[66:67], v[74:75]
	v_mad_i64_i32 v[80:81], s[6:7], v80, s54, v[156:157]
	v_pk_mul_f32 v[70:71], v[70:71], v[82:83]
	v_pk_mul_f32 v[68:69], v[68:69], v[76:77]
	v_pk_mul_f32 v[72:73], v[66:67], v[84:85]
	v_pk_mul_f32 v[66:67], v[64:65], v[78:79]
	v_lshl_add_u64 v[80:81], v[80:81], 0, v[118:119]
	v_cvt_pk_bf16_f32 v64, v68, v69
	v_cvt_pk_bf16_f32 v65, v70, v71
	v_cvt_pk_bf16_f32 v66, v66, v67
	v_cvt_pk_bf16_f32 v67, v72, v73
	v_pk_mul_f32 v[58:59], v[146:147], v[58:59] op_sel_hi:[0,1]
	v_pk_mul_f32 v[56:57], v[146:147], v[56:57] op_sel_hi:[0,1]
	global_store_dwordx4 v[80:81], v[64:67], off
	v_pk_mul_f32 v[62:63], v[146:147], v[62:63] op_sel_hi:[0,1]
	v_pk_mul_f32 v[60:61], v[146:147], v[60:61] op_sel_hi:[0,1]
	v_mul_f32_e32 v67, 0xbfb8aa3b, v56
	v_mul_f32_e32 v71, 0xbfb8aa3b, v58
	v_mul_f32_e32 v66, 0xbfb8aa3b, v60
	v_exp_f32_e32 v67, v67
	v_mul_f32_e32 v68, 0xbfb8aa3b, v61
	v_mul_f32_e32 v69, 0xbfb8aa3b, v57
	v_mul_f32_e32 v70, 0xbfb8aa3b, v62
	v_exp_f32_e32 v71, v71
	v_mul_f32_e32 v72, 0xbfb8aa3b, v63
	v_mul_f32_e32 v73, 0xbfb8aa3b, v59
	v_exp_f32_e32 v66, v66
	v_exp_f32_e32 v68, v68
	v_exp_f32_e32 v69, v69
	v_exp_f32_e32 v70, v70
	v_exp_f32_e32 v72, v72
	v_exp_f32_e32 v73, v73
	v_pk_mul_f32 v[52:53], v[146:147], v[52:53] op_sel_hi:[0,1]
	v_pk_mul_f32 v[54:55], v[146:147], v[54:55] op_sel_hi:[0,1]
	v_pk_mul_f32 v[52:53], v[52:53], v[60:61]
	v_add_f32_e32 v61, 1.0, v67
	v_add_f32_e32 v67, 1.0, v71
	v_pk_mul_f32 v[54:55], v[54:55], v[62:63]
	v_add_f32_e32 v60, 1.0, v66
	v_rcp_f32_e32 v62, v61
	v_add_f32_e32 v61, 1.0, v68
	v_add_f32_e32 v63, 1.0, v69
	v_add_f32_e32 v66, 1.0, v70
	v_rcp_f32_e32 v68, v67
	v_add_f32_e32 v67, 1.0, v72
	v_add_f32_e32 v69, 1.0, v73
	v_rcp_f32_e32 v60, v60
	v_rcp_f32_e32 v61, v61
	v_rcp_f32_e32 v63, v63
	v_rcp_f32_e32 v66, v66
	v_rcp_f32_e32 v67, v67
	v_rcp_f32_e32 v69, v69
	v_pk_mul_f32 v[50:51], v[146:147], v[50:51] op_sel_hi:[0,1]
	v_pk_mul_f32 v[48:49], v[146:147], v[48:49] op_sel_hi:[0,1]
	v_add_u32_e32 v64, 0x80, v145
	v_pk_mul_f32 v[48:49], v[48:49], v[56:57]
	v_pk_mul_f32 v[50:51], v[50:51], v[58:59]
	v_mad_i64_i32 v[64:65], s[6:7], v64, s54, v[156:157]
	v_pk_mul_f32 v[54:55], v[54:55], v[66:67]
	v_pk_mul_f32 v[52:53], v[52:53], v[60:61]
	v_pk_mul_f32 v[56:57], v[50:51], v[68:69]
	v_pk_mul_f32 v[50:51], v[48:49], v[62:63]
	v_lshl_add_u64 v[64:65], v[64:65], 0, v[118:119]
	v_cvt_pk_bf16_f32 v48, v52, v53
	v_cvt_pk_bf16_f32 v49, v54, v55
	v_cvt_pk_bf16_f32 v50, v50, v51
	v_cvt_pk_bf16_f32 v51, v56, v57
	v_pk_mul_f32 v[42:43], v[144:145], v[42:43] op_sel_hi:[0,1]
	v_pk_mul_f32 v[40:41], v[144:145], v[40:41] op_sel_hi:[0,1]
	global_store_dwordx4 v[64:65], v[48:51], off
	v_pk_mul_f32 v[46:47], v[144:145], v[46:47] op_sel_hi:[0,1]
	v_pk_mul_f32 v[44:45], v[144:145], v[44:45] op_sel_hi:[0,1]
	v_mul_f32_e32 v51, 0xbfb8aa3b, v40
	v_mul_f32_e32 v55, 0xbfb8aa3b, v42
; __device__ __forceinline__ unsigned cvtpk(float lo, float hi) { f32x2_t v = {lo, hi}; bf16x2_t b = __builtin_convertvector(v, bf16x2_t); return __builtin_bit_cast(unsigned, b); }
; #define PG8_BAR __builtin_amdgcn_s_barrier()
;     __device__ __forceinline__ void operator()(const f32x4 (&acc)[2][2][4][2], const Unit& u, int wr, int wc, int fr, int fq, const float (&pre)[8]) const {
;     ...
;         for (int ai = 0; ai < 2; ++ai)
; #pragma unroll
;             for (int m = 0; m < 4; ++m) {
;                 bf16_t* rowp = O + (size_t)(row0 + ai * HALF + m * 16) * ldc + col0;
;                 const float rs = pre[ai * 4 + m];
;                 const f32x4 g0 = acc[ai][0][m][0] * rs, g1 = acc[ai][0][m][1] * rs, u0 = acc[ai][1][m][0] * rs, u1 = acc[ai][1][m][1] * rs;
;                 const f32x4 t0 = g0 * (-1.4426950408889634f), t1 = g1 * (-1.4426950408889634f);
;                 f32x4 e0, e1;
; #pragma unroll
;                 for (int j = 0; j < 4; ++j) { e0[j] = __builtin_amdgcn_exp2f(t0[j]); e1[j] = __builtin_amdgcn_exp2f(t1[j]); }
;                 const f32x4 d0 = e0 + 1.0f, d1 = e1 + 1.0f, p0 = g0 * u0, p1 = g1 * u1;
;                 f32x4 r0, r1;
; #pragma unroll
;                 for (int j = 0; j < 4; ++j) { r0[j] = __builtin_amdgcn_rcpf(d0[j]); r1[j] = __builtin_amdgcn_rcpf(d1[j]); }
;                 const f32x4 o0 = p0 * r0, o1 = p1 * r1;
;                 u32x4 w;
;                 w.x = cvtpk(o0[0], o0[1]); w.y = cvtpk(o0[2], o0[3]); w.z = cvtpk(o1[0], o1[1]); w.w = cvtpk(o1[2], o1[3]);
;                 *(u32x4*)rowp = w;
; template <class Epi>
; __device__ __forceinline__ void gemm_phase(PG8_LAS unsigned char* lds, const Gemm g, const StaticOrder& S, const Epi& E, const int wave_s) {
;     ...
;         if (!has_next) break;
; #pragma unroll
;         for (int a = 0; a < 2; ++a)
; #pragma unroll
;             for (int b = 0; b < 2; ++b)
; #pragma unroll
;                 for (int m = 0; m < 4; ++m)
; #pragma unroll
;                     for (int n = 0; n < 2; ++n) acc[a][b][m][n] = (f32x4){0.f, 0.f, 0.f, 0.f};
;         cur = nxt; cA = nA; cB = nB; ++ui;
;         if (wr == 1) PG8_BAR;
	v_mul_f32_e32 v50, 0xbfb8aa3b, v44
	v_exp_f32_e32 v51, v51
	v_mul_f32_e32 v52, 0xbfb8aa3b, v45
	v_mul_f32_e32 v53, 0xbfb8aa3b, v41
	v_mul_f32_e32 v54, 0xbfb8aa3b, v46
	v_exp_f32_e32 v55, v55
	v_mul_f32_e32 v56, 0xbfb8aa3b, v47
	v_mul_f32_e32 v57, 0xbfb8aa3b, v43
	v_exp_f32_e32 v50, v50
	v_exp_f32_e32 v52, v52
	v_exp_f32_e32 v53, v53
	v_exp_f32_e32 v54, v54
	v_exp_f32_e32 v56, v56
	v_exp_f32_e32 v57, v57
	v_pk_mul_f32 v[36:37], v[144:145], v[36:37] op_sel_hi:[0,1]
	v_pk_mul_f32 v[38:39], v[144:145], v[38:39] op_sel_hi:[0,1]
	v_pk_mul_f32 v[36:37], v[36:37], v[44:45]
	v_add_f32_e32 v45, 1.0, v51
	v_add_f32_e32 v51, 1.0, v55
	v_pk_mul_f32 v[38:39], v[38:39], v[46:47]
	v_add_f32_e32 v44, 1.0, v50
	v_rcp_f32_e32 v46, v45
	v_add_f32_e32 v45, 1.0, v52
	v_add_f32_e32 v47, 1.0, v53
	v_add_f32_e32 v50, 1.0, v54
	v_rcp_f32_e32 v52, v51
	v_add_f32_e32 v51, 1.0, v56
	v_add_f32_e32 v53, 1.0, v57
	v_rcp_f32_e32 v44, v44
	v_rcp_f32_e32 v45, v45
	v_rcp_f32_e32 v47, v47
	v_rcp_f32_e32 v50, v50
	v_rcp_f32_e32 v51, v51
	v_rcp_f32_e32 v53, v53
	v_pk_mul_f32 v[34:35], v[144:145], v[34:35] op_sel_hi:[0,1]
	v_pk_mul_f32 v[32:33], v[144:145], v[32:33] op_sel_hi:[0,1]
	v_add_u32_e32 v48, 0x90, v145
	v_pk_mul_f32 v[32:33], v[32:33], v[40:41]
	v_pk_mul_f32 v[34:35], v[34:35], v[42:43]
	v_mad_i64_i32 v[48:49], s[6:7], v48, s54, v[156:157]
	v_pk_mul_f32 v[38:39], v[38:39], v[50:51]
	v_pk_mul_f32 v[36:37], v[36:37], v[44:45]
	v_pk_mul_f32 v[40:41], v[34:35], v[52:53]
	v_pk_mul_f32 v[34:35], v[32:33], v[46:47]
	v_lshl_add_u64 v[48:49], v[48:49], 0, v[118:119]
	v_cvt_pk_bf16_f32 v32, v36, v37
	v_cvt_pk_bf16_f32 v33, v38, v39
	v_cvt_pk_bf16_f32 v34, v34, v35
	v_cvt_pk_bf16_f32 v35, v40, v41
	v_pk_mul_f32 v[26:27], v[142:143], v[26:27] op_sel_hi:[0,1]
	v_pk_mul_f32 v[24:25], v[142:143], v[24:25] op_sel_hi:[0,1]
	global_store_dwordx4 v[48:49], v[32:35], off
	v_pk_mul_f32 v[30:31], v[142:143], v[30:31] op_sel_hi:[0,1]
	v_pk_mul_f32 v[28:29], v[142:143], v[28:29] op_sel_hi:[0,1]
	v_mul_f32_e32 v35, 0xbfb8aa3b, v24
	v_mul_f32_e32 v39, 0xbfb8aa3b, v26
	v_mul_f32_e32 v34, 0xbfb8aa3b, v28
	v_exp_f32_e32 v35, v35
	v_mul_f32_e32 v36, 0xbfb8aa3b, v29
	v_mul_f32_e32 v37, 0xbfb8aa3b, v25
	v_mul_f32_e32 v38, 0xbfb8aa3b, v30
	v_exp_f32_e32 v39, v39
	v_mul_f32_e32 v40, 0xbfb8aa3b, v31
	v_mul_f32_e32 v41, 0xbfb8aa3b, v27
	v_exp_f32_e32 v34, v34
	v_exp_f32_e32 v36, v36
	v_exp_f32_e32 v37, v37
	v_exp_f32_e32 v38, v38
	v_exp_f32_e32 v40, v40
	v_exp_f32_e32 v41, v41
	v_pk_mul_f32 v[20:21], v[142:143], v[20:21] op_sel_hi:[0,1]
	v_pk_mul_f32 v[22:23], v[142:143], v[22:23] op_sel_hi:[0,1]
	v_pk_mul_f32 v[20:21], v[20:21], v[28:29]
	v_add_f32_e32 v29, 1.0, v35
	v_add_f32_e32 v35, 1.0, v39
	v_pk_mul_f32 v[22:23], v[22:23], v[30:31]
	v_add_f32_e32 v28, 1.0, v34
	v_rcp_f32_e32 v30, v29
	v_add_f32_e32 v29, 1.0, v36
	v_add_f32_e32 v31, 1.0, v37
	v_add_f32_e32 v34, 1.0, v38
	v_rcp_f32_e32 v36, v35
	v_add_f32_e32 v35, 1.0, v40
	v_add_f32_e32 v37, 1.0, v41
	v_rcp_f32_e32 v28, v28
	v_rcp_f32_e32 v29, v29
	v_rcp_f32_e32 v31, v31
	v_rcp_f32_e32 v34, v34
	v_rcp_f32_e32 v35, v35
	v_rcp_f32_e32 v37, v37
	v_pk_mul_f32 v[18:19], v[142:143], v[18:19] op_sel_hi:[0,1]
	v_pk_mul_f32 v[16:17], v[142:143], v[16:17] op_sel_hi:[0,1]
	v_add_u32_e32 v32, 0xa0, v145
	v_pk_mul_f32 v[16:17], v[16:17], v[24:25]
	v_pk_mul_f32 v[18:19], v[18:19], v[26:27]
	v_mad_i64_i32 v[32:33], s[6:7], v32, s54, v[156:157]
	v_pk_mul_f32 v[22:23], v[22:23], v[34:35]
	v_pk_mul_f32 v[20:21], v[20:21], v[28:29]
	v_pk_mul_f32 v[24:25], v[18:19], v[36:37]
	v_pk_mul_f32 v[18:19], v[16:17], v[30:31]
	v_lshl_add_u64 v[32:33], v[32:33], 0, v[118:119]
	v_cvt_pk_bf16_f32 v16, v20, v21
	v_cvt_pk_bf16_f32 v17, v22, v23
	v_cvt_pk_bf16_f32 v18, v18, v19
	v_cvt_pk_bf16_f32 v19, v24, v25
	v_pk_mul_f32 v[10:11], v[140:141], v[10:11] op_sel_hi:[0,1]
	v_pk_mul_f32 v[8:9], v[140:141], v[8:9] op_sel_hi:[0,1]
	global_store_dwordx4 v[32:33], v[16:19], off
	v_pk_mul_f32 v[14:15], v[140:141], v[14:15] op_sel_hi:[0,1]
	v_pk_mul_f32 v[12:13], v[140:141], v[12:13] op_sel_hi:[0,1]
	v_mul_f32_e32 v19, 0xbfb8aa3b, v8
	v_mul_f32_e32 v23, 0xbfb8aa3b, v10
	v_mul_f32_e32 v18, 0xbfb8aa3b, v12
	v_exp_f32_e32 v19, v19
	v_mul_f32_e32 v20, 0xbfb8aa3b, v13
	v_mul_f32_e32 v21, 0xbfb8aa3b, v9
	v_mul_f32_e32 v22, 0xbfb8aa3b, v14
	v_exp_f32_e32 v23, v23
	v_mul_f32_e32 v24, 0xbfb8aa3b, v15
	v_mul_f32_e32 v25, 0xbfb8aa3b, v11
	v_exp_f32_e32 v18, v18
	v_exp_f32_e32 v20, v20
	v_exp_f32_e32 v21, v21
	v_exp_f32_e32 v22, v22
	v_exp_f32_e32 v24, v24
	v_exp_f32_e32 v25, v25
	v_pk_mul_f32 v[4:5], v[140:141], v[4:5] op_sel_hi:[0,1]
	v_pk_mul_f32 v[6:7], v[140:141], v[6:7] op_sel_hi:[0,1]
	v_pk_mul_f32 v[4:5], v[4:5], v[12:13]
	v_add_f32_e32 v13, 1.0, v19
	v_add_f32_e32 v19, 1.0, v23
	v_pk_mul_f32 v[6:7], v[6:7], v[14:15]
	v_add_f32_e32 v12, 1.0, v18
	v_rcp_f32_e32 v14, v13
	v_add_f32_e32 v13, 1.0, v20
	v_add_f32_e32 v15, 1.0, v21
	v_add_f32_e32 v18, 1.0, v22
	v_rcp_f32_e32 v20, v19
	v_add_f32_e32 v19, 1.0, v24
	v_add_f32_e32 v21, 1.0, v25
	v_rcp_f32_e32 v12, v12
	v_rcp_f32_e32 v13, v13
	v_rcp_f32_e32 v15, v15
	v_rcp_f32_e32 v18, v18
	v_rcp_f32_e32 v19, v19
	v_rcp_f32_e32 v21, v21
	v_pk_mul_f32 v[2:3], v[140:141], v[2:3] op_sel_hi:[0,1]
	v_pk_mul_f32 v[0:1], v[140:141], v[0:1] op_sel_hi:[0,1]
	v_add_u32_e32 v16, 0xb0, v145
	v_pk_mul_f32 v[0:1], v[0:1], v[8:9]
	v_pk_mul_f32 v[2:3], v[2:3], v[10:11]
	v_mad_i64_i32 v[16:17], s[6:7], v16, s54, v[156:157]
	v_pk_mul_f32 v[6:7], v[6:7], v[18:19]
	v_pk_mul_f32 v[4:5], v[4:5], v[12:13]
	v_pk_mul_f32 v[8:9], v[2:3], v[20:21]
	v_pk_mul_f32 v[2:3], v[0:1], v[14:15]
	v_lshl_add_u64 v[16:17], v[16:17], 0, v[118:119]
	v_cvt_pk_bf16_f32 v0, v4, v5
	v_cvt_pk_bf16_f32 v1, v6, v7
	v_cvt_pk_bf16_f32 v2, v2, v3
	v_cvt_pk_bf16_f32 v3, v8, v9
	s_and_b64 vcc, exec, s[42:43]
	s_mov_b64 s[6:7], -1
	global_store_dwordx4 v[16:17], v[0:3], off
	s_cbranch_vccnz .LBB0_941
	s_andn2_b64 vcc, exec, s[40:41]
	s_cbranch_vccnz .LBB0_940
	s_barrier
	s_branch .LBB0_940

; __device__ __forceinline__ unsigned cvtpk(float lo, float hi) { f32x2_t v = {lo, hi}; bf16x2_t b = __builtin_convertvector(v, bf16x2_t); return __builtin_bit_cast(unsigned, b); }
; __device__ __forceinline__ void transpose_item(const float* W, int K, int N, bf16_t* WT, int mode, const float* kscale, float* scr, int item, int nblk, int lane) {
;     ...
;     for (int i = 0; i < 32; ++i) { const int kk = 2 * i + (lane >> 5); float v = wv[i]; if (kscale) v *= kscale[k0 + kk]; scr[kk * 33 + (lane & 31)] = v; }
;     __builtin_amdgcn_s_waitcnt(0); asm volatile("" ::: "memory");
;     const int c = lane & 7;
;     int drow0 = n0; if (mode == 1) drow0 = (n0 / 128) * 256 + (n0 % 128); else if (mode == 2) drow0 = (n0 / 128) * 256 + 128 + (n0 % 128);
; #pragma unroll
;     for (int j = 0; j < 4; ++j) { const int n = (lane >> 3) + 8 * j; const float* s = scr + (8 * c) * 33 + n;
;         u32x4 o; o.x = cvtpk(s[0 * 33], s[1 * 33]); o.y = cvtpk(s[2 * 33], s[3 * 33]); o.z = cvtpk(s[4 * 33], s[5 * 33]); o.w = cvtpk(s[6 * 33], s[7 * 33]);
;         *(u32x4*)(WT + (size_t)(drow0 + n) * K + k0 + 8 * c) = o; }
;     __builtin_amdgcn_s_waitcnt(0); asm volatile("" ::: "memory");
.LBB0_960:
	s_mul_hi_i32 s5, s4, 0x2900000
	s_mul_i32 s4, s4, 0x2900000
	s_add_u32 s6, s16, s4
	s_addc_u32 s7, s25, s5
	s_bfe_i32 s4, s8, 0x80000
	s_bfe_u32 s4, s4, 0x2000d
	s_add_i32 s8, s8, s4
	s_bfe_u32 s5, s3, 0x70018
	s_bfe_i32 s4, s8, 0x80000
	s_add_i32 s5, s3, s5
	s_sext_i32_i16 s4, s4
	s_and_b32 s5, s5, 0xff80
	ds_write_b32 v61, v4
	ds_write_b32 v62, v5
	s_waitcnt vmcnt(0) expcnt(0) lgkmcnt(0)
	s_lshl_b32 s4, s4, 6
	s_sub_i32 s3, s3, s5
	s_and_b32 s4, s4, 0xffffff00
	s_sext_i32_i16 s3, s3
	ds_read2_b32 v[8:9], v28 offset0:33 offset1:41
	ds_read2_b32 v[10:11], v28 offset1:8
	ds_read2_b32 v[12:13], v28 offset0:66 offset1:74
	ds_read2_b32 v[14:15], v28 offset0:99 offset1:107
	ds_read2_b32 v[16:17], v28 offset0:132 offset1:140
	ds_read2_b32 v[18:19], v28 offset0:165 offset1:173
	ds_read2_b32 v[20:21], v28 offset0:198 offset1:206
	ds_read2_b32 v[22:23], v28 offset0:231 offset1:239
	s_add_i32 s3, s4, s3
	s_lshl_b64 s[4:5], s[10:11], 1
	s_add_u32 s4, s6, s4
	v_or_b32_e32 v66, s3, v27
	s_addc_u32 s5, s7, s5
	v_lshlrev_b32_e32 v210, 1, v2
	v_ashrrev_i32_e32 v67, 31, v66
	v_lshl_add_u64 v[64:65], s[4:5], 0, v[210:211]
	v_lshlrev_b64 v[66:67], 11, v[66:67]
	s_waitcnt lgkmcnt(6)
	v_cvt_pk_bf16_f32 v4, v10, v8
	s_waitcnt lgkmcnt(4)
	v_cvt_pk_bf16_f32 v5, v12, v14
	s_waitcnt lgkmcnt(2)
	v_cvt_pk_bf16_f32 v6, v16, v18
	s_waitcnt lgkmcnt(0)
	v_cvt_pk_bf16_f32 v7, v20, v22
	v_lshl_add_u64 v[66:67], v[64:65], 0, v[66:67]
	v_or_b32_e32 v8, s3, v29
	global_store_dwordx4 v[66:67], v[4:7], off
	s_nop 1
	v_cvt_pk_bf16_f32 v4, v11, v9
	v_ashrrev_i32_e32 v9, 31, v8
	v_cvt_pk_bf16_f32 v5, v13, v15
	v_cvt_pk_bf16_f32 v6, v17, v19
	v_cvt_pk_bf16_f32 v7, v21, v23
	v_lshlrev_b64 v[8:9], 11, v[8:9]
	ds_read2_b32 v[10:11], v28 offset0:49 offset1:57
	ds_read2_b32 v[12:13], v28 offset0:16 offset1:24
	ds_read2_b32 v[14:15], v28 offset0:82 offset1:90
	ds_read2_b32 v[16:17], v28 offset0:115 offset1:123
	ds_read2_b32 v[18:19], v28 offset0:148 offset1:156
	ds_read2_b32 v[20:21], v28 offset0:181 offset1:189
	ds_read2_b32 v[22:23], v28 offset0:214 offset1:222
	ds_read2_b32 v[66:67], v28 offset0:247 offset1:255
	v_lshl_add_u64 v[8:9], v[64:65], 0, v[8:9]
	global_store_dwordx4 v[8:9], v[4:7], off
	v_or_b32_e32 v8, s3, v30
	v_ashrrev_i32_e32 v9, 31, v8
	v_lshlrev_b64 v[8:9], 11, v[8:9]
	s_waitcnt lgkmcnt(6)
	v_cvt_pk_bf16_f32 v4, v12, v10
	s_waitcnt lgkmcnt(4)
	v_cvt_pk_bf16_f32 v5, v14, v16
	s_waitcnt lgkmcnt(2)
	v_cvt_pk_bf16_f32 v6, v18, v20
	s_waitcnt lgkmcnt(0)
	v_cvt_pk_bf16_f32 v7, v22, v66
	v_lshl_add_u64 v[8:9], v[64:65], 0, v[8:9]
	global_store_dwordx4 v[8:9], v[4:7], off
	v_or_b32_e32 v8, s3, v31
	v_ashrrev_i32_e32 v9, 31, v8
	v_lshlrev_b64 v[8:9], 11, v[8:9]
	v_cvt_pk_bf16_f32 v4, v13, v11
	v_cvt_pk_bf16_f32 v5, v15, v17
	v_cvt_pk_bf16_f32 v6, v19, v21
	v_cvt_pk_bf16_f32 v7, v23, v67
	v_lshl_add_u64 v[8:9], v[64:65], 0, v[8:9]
	global_store_dwordx4 v[8:9], v[4:7], off
	s_waitcnt lgkmcnt(0)

; __device__ __forceinline__ void transpose_item(const float* W, int K, int N, bf16_t* WT, int mode, const float* kscale, float* scr, int item, int nblk, int lane) {
;     const int kb = item / nblk, nb = item % nblk, k0 = 64 * kb, n0 = 32 * nb;
;     const int nn = n0 + (lane & 31);
;     float wv[32];
; #pragma unroll
;     for (int i = 0; i < 32; ++i) { const int kk = 2 * i + (lane >> 5); wv[i] = (nn < N) ? W[(size_t)(k0 + kk) * N + nn] : 0.f; }
; __global__ void __launch_bounds__(NWAVES * 64, 2) mega_fwd(Args args) {
;     ...
;             for (int it = gw; it < 2 * PER_L; it += NGW) {
;                 const int l = it / PER_L; int r = it % PER_L;
;                 if (r < I_G) { transpose_item(INF(4, l, D * FF), D, FF, WPTR(l, WL_GU1), 1, INF(2, l, D), scr, r, 88, c.lane); continue; } r -= I_G;
;                 if (r < I_G) { transpose_item(INF(5, l, D * FF), D, FF, WPTR(l, WL_GU1), 2, INF(2, l, D), scr, r, 88, c.lane); continue; } r -= I_G;
;                 if (r < I_D) { transpose_item(INF(6, l, D * FF), FF, D, WPTR(l, WL_D1), 0, nullptr, scr, r, 32, c.lane); continue; } r -= I_D;
;                 if (r < I_G) { transpose_item(INF(21, l, D * FF), D, FF, WPTR(l, WL_GU2), 1, INF(19, l, D), scr, r, 88, c.lane); continue; } r -= I_G;
;                 if (r < I_G) { transpose_item(INF(22, l, D * FF), D, FF, WPTR(l, WL_GU2), 2, INF(19, l, D), scr, r, 88, c.lane); continue; } r -= I_G;
;                 if (r < I_D) { transpose_item(INF(23, l, D * FF), FF, D, WPTR(l, WL_D2), 0, nullptr, scr, r, 32, c.lane); continue; } r -= I_D;
;                 if (r < I_IN) { transpose_item(INF(9, l, D * DIN), D, DIN, WPTR(l, WL_IN), 0, INF(7, l, D), scr, r, 64, c.lane); continue; } r -= I_IN;
;                 if (r < I_Q) { transpose_item(INF(11, l, 256 * 768), 256, 768, WPTR(l, WL_Q), 0, INF(10, l, 256), scr, r, 24, c.lane); continue; } r -= I_Q;
;                 if (r < I_KV) { transpose_item(INF(13, l, 128 * 1024), 128, 1024, WPTR(l, WL_KV), 0, INF(12, l, 128), scr, r, 32, c.lane); continue; } r -= I_KV;
;                 transpose_item(INF(18, l, D * D), D, D, WPTR(l, WL_OUT), 0, nullptr, scr, r, 32, c.lane);
.LBB0_962:
	s_mul_hi_i32 s3, s24, 0x33af3e2f
	s_lshr_b32 s4, s3, 31
	s_ashr_i32 s3, s3, 11
	s_add_i32 s4, s3, s4
	s_mul_i32 s3, s4, 0xffffd860
	s_add_i32 s28, s24, s3
	s_cmpk_gt_i32 s28, 0x57f
	s_mov_b64 s[6:7], -1
	s_cbranch_scc0 .LBB0_1268
	s_cmpk_gt_u32 s28, 0xaff
	s_cbranch_scc0 .LBB0_1241
	s_cmpk_gt_u32 s28, 0x107f
	s_cbranch_scc0 .LBB0_1238
	s_cmpk_gt_u32 s28, 0x15ff
	s_cbranch_scc0 .LBB0_1211
	s_cmpk_gt_u32 s28, 0x1b7f
	s_cbranch_scc0 .LBB0_1184
	s_cmpk_gt_u32 s28, 0x20ff
	s_cbranch_scc0 .LBB0_1181
	s_cmpk_gt_u32 s28, 0x24ff
	s_cbranch_scc0 .LBB0_1090
	s_cmpk_gt_u32 s28, 0x255f
	s_cbranch_scc0 .LBB0_1063
	s_ashr_i32 s5, s4, 31
	s_mul_i32 s3, s4, 0x2900000
	s_mul_hi_i32 s6, s4, 0x2900000
	s_add_u32 s3, s78, s3
	s_addc_u32 s8, s79, s6
	s_cmpk_gt_u32 s28, 0x259f
	s_mov_b64 s[6:7], -1
	s_cbranch_scc0 .LBB0_972
	s_load_dwordx2 s[6:7], s[0:1], 0x90
	s_lshl_b64 s[10:11], s[4:5], 22
	s_mul_i32 s9, s4, 0xffffb0c0
	s_waitcnt lgkmcnt(0)
	s_add_u32 s10, s6, s10
	s_addc_u32 s11, s7, s11
	s_add_i32 s7, s31, s9
	s_and_b32 s6, s27, 0x3e0
	s_addk_i32 s7, 0xcac0
	s_and_b32 s7, s7, 0x1ffc0
	v_or_b32_e32 v4, s6, v25
	v_or_b32_e32 v6, s7, v0
	v_lshlrev_b32_e32 v210, 2, v4
	v_lshl_add_u64 v[4:5], s[10:11], 0, v[210:211]
	v_lshlrev_b32_e32 v210, 12, v6
	v_lshl_add_u64 v[4:5], v[4:5], 0, v[210:211]
	s_movk_i32 s9, 0x2000
	v_add_co_u32_e32 v6, vcc, s9, v4
	s_movk_i32 s9, 0x4000
	s_nop 0
	v_addc_co_u32_e32 v7, vcc, 0, v5, vcc
	v_add_co_u32_e32 v8, vcc, s9, v4
	s_movk_i32 s9, 0x6000
	s_nop 0
	v_addc_co_u32_e32 v9, vcc, 0, v5, vcc
	v_add_co_u32_e32 v10, vcc, s9, v4
	s_mov_b32 s9, 0x8000
	s_nop 0
	v_addc_co_u32_e32 v11, vcc, 0, v5, vcc
	v_add_co_u32_e32 v12, vcc, s9, v4
	s_mov_b32 s9, 0xa000
	s_nop 0
	v_addc_co_u32_e32 v13, vcc, 0, v5, vcc
	v_add_co_u32_e32 v14, vcc, s9, v4
	s_mov_b32 s9, 0xc000
	s_nop 0
	v_addc_co_u32_e32 v15, vcc, 0, v5, vcc
	v_add_co_u32_e32 v16, vcc, s9, v4
	s_mov_b32 s9, 0xe000
	s_nop 0
	v_addc_co_u32_e32 v17, vcc, 0, v5, vcc
	v_add_co_u32_e32 v18, vcc, s9, v4
	s_mov_b32 s9, 0x12000
	s_nop 0
	v_addc_co_u32_e32 v19, vcc, 0, v5, vcc
	global_load_dword v22, v[4:5], off
	global_load_dword v23, v[6:7], off
	global_load_dword v63, v[8:9], off
	global_load_dword v64, v[10:11], off
	global_load_dword v65, v[12:13], off
	global_load_dword v66, v[14:15], off
	global_load_dword v67, v[16:17], off
	global_load_dword v68, v[18:19], off
	v_add_co_u32_e32 v6, vcc, s89, v4
	s_lshl_b32 s7, s7, 1
	s_nop 0
	v_addc_co_u32_e32 v7, vcc, 0, v5, vcc
	v_add_co_u32_e32 v8, vcc, s9, v4
	s_mov_b32 s9, 0x14000
	s_nop 0
	v_addc_co_u32_e32 v9, vcc, 0, v5, vcc
	v_add_co_u32_e32 v10, vcc, s9, v4
	s_mov_b32 s9, 0x18000
	s_nop 0
	v_addc_co_u32_e32 v11, vcc, 0, v5, vcc
	v_add_co_u32_e32 v12, vcc, s90, v4
	s_add_u32 s10, s3, s7
	s_nop 0
	v_addc_co_u32_e32 v13, vcc, 0, v5, vcc
	v_add_co_u32_e32 v14, vcc, s9, v4
	s_mov_b32 s9, 0x1a000
	s_nop 0
	v_addc_co_u32_e32 v15, vcc, 0, v5, vcc
	v_add_co_u32_e32 v16, vcc, s9, v4
	s_mov_b32 s9, 0x1c000
	s_nop 0
	v_addc_co_u32_e32 v17, vcc, 0, v5, vcc
	v_add_co_u32_e32 v18, vcc, s9, v4
	s_mov_b32 s9, 0x1e000
	s_nop 0
	v_addc_co_u32_e32 v19, vcc, 0, v5, vcc
	v_add_co_u32_e32 v20, vcc, s9, v4
	s_mov_b32 s9, 0x20000
	s_nop 0
	v_addc_co_u32_e32 v21, vcc, 0, v5, vcc
	global_load_dword v69, v[6:7], off
	global_load_dword v70, v[8:9], off
	global_load_dword v71, v[10:11], off
	global_load_dword v72, v[12:13], off
	global_load_dword v73, v[14:15], off
	global_load_dword v74, v[16:17], off
	global_load_dword v75, v[18:19], off
	global_load_dword v76, v[20:21], off
	v_add_co_u32_e32 v6, vcc, s9, v4
	s_mov_b32 s9, 0x22000
	s_nop 0
	v_addc_co_u32_e32 v7, vcc, 0, v5, vcc
	v_add_co_u32_e32 v8, vcc, s9, v4
	s_mov_b32 s9, 0x24000
	s_nop 0
	v_addc_co_u32_e32 v9, vcc, 0, v5, vcc
	v_add_co_u32_e32 v10, vcc, s9, v4
	s_mov_b32 s9, 0x26000
	s_nop 0
	v_addc_co_u32_e32 v11, vcc, 0, v5, vcc
	v_add_co_u32_e32 v12, vcc, s9, v4
	s_mov_b32 s9, 0x28000
	s_nop 0
	v_addc_co_u32_e32 v13, vcc, 0, v5, vcc
	v_add_co_u32_e32 v14, vcc, s9, v4
	s_mov_b32 s9, 0x2a000
	s_nop 0
	v_addc_co_u32_e32 v15, vcc, 0, v5, vcc
	v_add_co_u32_e32 v16, vcc, s9, v4
	s_mov_b32 s9, 0x2c000
	s_nop 0
	v_addc_co_u32_e32 v17, vcc, 0, v5, vcc
	v_add_co_u32_e32 v18, vcc, s9, v4
	s_mov_b32 s9, 0x2e000
	s_nop 0
	v_addc_co_u32_e32 v19, vcc, 0, v5, vcc
	v_add_co_u32_e32 v20, vcc, s9, v4
	s_mov_b32 s9, 0x30000
	s_nop 0
	v_addc_co_u32_e32 v21, vcc, 0, v5, vcc
	global_load_dword v77, v[6:7], off
	global_load_dword v78, v[8:9], off
	global_load_dword v79, v[10:11], off
	global_load_dword v80, v[12:13], off
	global_load_dword v81, v[14:15], off
	global_load_dword v82, v[16:17], off
	global_load_dword v83, v[18:19], off
	s_nop 0
	global_load_dword v20, v[20:21], off
	v_add_co_u32_e32 v6, vcc, s9, v4
	s_mov_b32 s9, 0x32000
	s_nop 0
	v_addc_co_u32_e32 v7, vcc, 0, v5, vcc
	v_add_co_u32_e32 v8, vcc, s9, v4
	s_mov_b32 s9, 0x34000
	s_nop 0
	v_addc_co_u32_e32 v9, vcc, 0, v5, vcc
	v_add_co_u32_e32 v10, vcc, s9, v4
	s_mov_b32 s9, 0x36000
	s_nop 0
	v_addc_co_u32_e32 v11, vcc, 0, v5, vcc
	v_add_co_u32_e32 v12, vcc, s9, v4
	s_mov_b32 s9, 0x38000
	s_nop 0
	v_addc_co_u32_e32 v13, vcc, 0, v5, vcc
	v_add_co_u32_e32 v14, vcc, s9, v4
	s_mov_b32 s9, 0x3a000
	s_nop 0
	v_addc_co_u32_e32 v15, vcc, 0, v5, vcc
	v_add_co_u32_e32 v16, vcc, s9, v4
	s_mov_b32 s9, 0x3c000
	s_nop 0
	v_addc_co_u32_e32 v17, vcc, 0, v5, vcc
	v_add_co_u32_e32 v18, vcc, s9, v4
	s_mov_b32 s9, 0x3e000
	s_nop 0
	v_addc_co_u32_e32 v19, vcc, 0, v5, vcc
	v_add_co_u32_e32 v4, vcc, s9, v4
	s_addc_u32 s11, s8, 0
	s_nop 0
	v_addc_co_u32_e32 v5, vcc, 0, v5, vcc
	global_load_dword v6, v[6:7], off
	s_nop 0
	global_load_dword v7, v[8:9], off
	s_nop 0
	global_load_dword v8, v[10:11], off
	global_load_dword v9, v[12:13], off
	s_nop 0
	global_load_dword v10, v[14:15], off
	global_load_dword v11, v[16:17], off
	global_load_dword v12, v[18:19], off
	s_nop 0
	global_load_dword v4, v[4:5], off
	v_add_u32_e32 v5, 0x400, v26
	s_waitcnt vmcnt(30)
; __device__ __forceinline__ unsigned cvtpk(float lo, float hi) { f32x2_t v = {lo, hi}; bf16x2_t b = __builtin_convertvector(v, bf16x2_t); return __builtin_bit_cast(unsigned, b); }
; __device__ __forceinline__ void transpose_item(const float* W, int K, int N, bf16_t* WT, int mode, const float* kscale, float* scr, int item, int nblk, int lane) {
;     ...
;     for (int i = 0; i < 32; ++i) { const int kk = 2 * i + (lane >> 5); float v = wv[i]; if (kscale) v *= kscale[k0 + kk]; scr[kk * 33 + (lane & 31)] = v; }
;     __builtin_amdgcn_s_waitcnt(0); asm volatile("" ::: "memory");
;     const int c = lane & 7;
;     int drow0 = n0; if (mode == 1) drow0 = (n0 / 128) * 256 + (n0 % 128); else if (mode == 2) drow0 = (n0 / 128) * 256 + 128 + (n0 % 128);
; #pragma unroll
;     for (int j = 0; j < 4; ++j) { const int n = (lane >> 3) + 8 * j; const float* s = scr + (8 * c) * 33 + n;
;         u32x4 o; o.x = cvtpk(s[0 * 33], s[1 * 33]); o.y = cvtpk(s[2 * 33], s[3 * 33]); o.z = cvtpk(s[4 * 33], s[5 * 33]); o.w = cvtpk(s[6 * 33], s[7 * 33]);
;         *(u32x4*)(WT + (size_t)(drow0 + n) * K + k0 + 8 * c) = o; }
;     __builtin_amdgcn_s_waitcnt(0); asm volatile("" ::: "memory");
	ds_write2_b32 v26, v22, v23 offset1:66
	s_waitcnt vmcnt(28)
	ds_write2_b32 v26, v63, v64 offset0:132 offset1:198
	s_waitcnt vmcnt(26)
	ds_write2_b32 v5, v65, v66 offset0:8 offset1:74
	s_waitcnt vmcnt(24)
	ds_write2_b32 v5, v67, v68 offset0:140 offset1:206
	v_add_u32_e32 v5, 0x800, v26
	s_waitcnt vmcnt(22)
	ds_write2_b32 v5, v69, v70 offset0:16 offset1:82
	s_waitcnt vmcnt(20)
	ds_write2_b32 v5, v71, v72 offset0:148 offset1:214
	v_add_u32_e32 v5, 0xc00, v26
	s_waitcnt vmcnt(18)
	ds_write2_b32 v5, v73, v74 offset0:24 offset1:90
	s_waitcnt vmcnt(16)
	ds_write2_b32 v5, v75, v76 offset0:156 offset1:222
	v_add_u32_e32 v5, 0x1000, v26
	s_waitcnt vmcnt(14)
	ds_write2_b32 v5, v77, v78 offset0:32 offset1:98
	s_waitcnt vmcnt(12)
	ds_write2_b32 v5, v79, v80 offset0:164 offset1:230
	v_add_u32_e32 v5, 0x1400, v26
	s_waitcnt vmcnt(10)
	ds_write2_b32 v5, v81, v82 offset0:40 offset1:106
	s_waitcnt vmcnt(8)
	ds_write2_b32 v5, v83, v20 offset0:172 offset1:238
	v_add_u32_e32 v5, 0x1800, v26
	s_waitcnt vmcnt(6)
	ds_write2_b32 v5, v6, v7 offset0:48 offset1:114
	s_waitcnt vmcnt(4)
	ds_write2_b32 v5, v8, v9 offset0:180 offset1:246
	v_add_u32_e32 v5, 0x1c00, v26
	s_waitcnt vmcnt(2)
	ds_write2_b32 v5, v10, v11 offset0:56 offset1:122
	s_waitcnt vmcnt(0)
	ds_write2_b32 v5, v12, v4 offset0:188 offset1:254
	s_waitcnt vmcnt(0) expcnt(0) lgkmcnt(0)
	ds_read2_b32 v[8:9], v28 offset0:33 offset1:41
	ds_read2_b32 v[10:11], v28 offset1:8
	ds_read2_b32 v[12:13], v28 offset0:66 offset1:74
	ds_read2_b32 v[14:15], v28 offset0:99 offset1:107
	ds_read2_b32 v[16:17], v28 offset0:132 offset1:140
	ds_read2_b32 v[18:19], v28 offset0:165 offset1:173
	ds_read2_b32 v[20:21], v28 offset0:198 offset1:206
	ds_read2_b32 v[22:23], v28 offset0:231 offset1:239
	v_lshlrev_b32_e32 v210, 1, v2
	v_lshl_add_u64 v[4:5], s[10:11], 0, v[210:211]
	s_mov_b64 s[10:11], 0x2700000
	v_lshl_add_u64 v[64:65], v[4:5], 0, s[10:11]
	s_waitcnt lgkmcnt(6)
	v_cvt_pk_bf16_f32 v4, v10, v8
	v_or_b32_e32 v8, s6, v27
	v_lshlrev_b32_e32 v210, 11, v8
	s_waitcnt lgkmcnt(4)
	v_cvt_pk_bf16_f32 v5, v12, v14
	s_waitcnt lgkmcnt(2)
	v_cvt_pk_bf16_f32 v6, v16, v18
	s_waitcnt lgkmcnt(0)
	v_cvt_pk_bf16_f32 v7, v20, v22
	v_lshl_add_u64 v[66:67], v[64:65], 0, v[210:211]
	global_store_dwordx4 v[66:67], v[4:7], off
	v_or_b32_e32 v8, s6, v29
	v_lshlrev_b32_e32 v210, 11, v8
	v_cvt_pk_bf16_f32 v4, v11, v9
	v_cvt_pk_bf16_f32 v5, v13, v15
	v_cvt_pk_bf16_f32 v6, v17, v19
	v_cvt_pk_bf16_f32 v7, v21, v23
	ds_read2_b32 v[10:11], v28 offset0:49 offset1:57
	ds_read2_b32 v[12:13], v28 offset0:16 offset1:24
	ds_read2_b32 v[14:15], v28 offset0:82 offset1:90
	ds_read2_b32 v[16:17], v28 offset0:115 offset1:123
	ds_read2_b32 v[18:19], v28 offset0:148 offset1:156
	ds_read2_b32 v[20:21], v28 offset0:181 offset1:189
	ds_read2_b32 v[22:23], v28 offset0:214 offset1:222
	ds_read2_b32 v[66:67], v28 offset0:247 offset1:255
	v_lshl_add_u64 v[8:9], v[64:65], 0, v[210:211]
	global_store_dwordx4 v[8:9], v[4:7], off
	v_or_b32_e32 v8, s6, v30
	v_lshlrev_b32_e32 v210, 11, v8
	s_waitcnt lgkmcnt(6)
	v_cvt_pk_bf16_f32 v4, v12, v10
	s_waitcnt lgkmcnt(4)
	v_cvt_pk_bf16_f32 v5, v14, v16
	s_waitcnt lgkmcnt(2)
	v_cvt_pk_bf16_f32 v6, v18, v20
	s_waitcnt lgkmcnt(0)
	v_cvt_pk_bf16_f32 v7, v22, v66
	v_lshl_add_u64 v[8:9], v[64:65], 0, v[210:211]
	global_store_dwordx4 v[8:9], v[4:7], off
	v_or_b32_e32 v8, s6, v31
	v_lshlrev_b32_e32 v210, 11, v8
	v_cvt_pk_bf16_f32 v4, v13, v11
	v_cvt_pk_bf16_f32 v5, v15, v17
	v_cvt_pk_bf16_f32 v6, v19, v21
	v_cvt_pk_bf16_f32 v7, v23, v67
	v_lshl_add_u64 v[8:9], v[64:65], 0, v[210:211]
	global_store_dwordx4 v[8:9], v[4:7], off
	s_waitcnt lgkmcnt(0)
	s_mov_b64 s[6:7], 0

; __device__ __forceinline__ unsigned cvtpk(float lo, float hi) { f32x2_t v = {lo, hi}; bf16x2_t b = __builtin_convertvector(v, bf16x2_t); return __builtin_bit_cast(unsigned, b); }
; __device__ __forceinline__ void transpose_item(const float* W, int K, int N, bf16_t* WT, int mode, const float* kscale, float* scr, int item, int nblk, int lane) {
;     ...
;     for (int i = 0; i < 32; ++i) { const int kk = 2 * i + (lane >> 5); float v = wv[i]; if (kscale) v *= kscale[k0 + kk]; scr[kk * 33 + (lane & 31)] = v; }
;     __builtin_amdgcn_s_waitcnt(0); asm volatile("" ::: "memory");
;     const int c = lane & 7;
;     int drow0 = n0; if (mode == 1) drow0 = (n0 / 128) * 256 + (n0 % 128); else if (mode == 2) drow0 = (n0 / 128) * 256 + 128 + (n0 % 128);
; #pragma unroll
;     for (int j = 0; j < 4; ++j) { const int n = (lane >> 3) + 8 * j; const float* s = scr + (8 * c) * 33 + n;
;         u32x4 o; o.x = cvtpk(s[0 * 33], s[1 * 33]); o.y = cvtpk(s[2 * 33], s[3 * 33]); o.z = cvtpk(s[4 * 33], s[5 * 33]); o.w = cvtpk(s[6 * 33], s[7 * 33]);
;         *(u32x4*)(WT + (size_t)(drow0 + n) * K + k0 + 8 * c) = o; }
;     __builtin_amdgcn_s_waitcnt(0); asm volatile("" ::: "memory");
.LBB0_1061:
	ds_write_b32 v61, v4
	ds_write_b32 v62, v5
	s_waitcnt vmcnt(0) expcnt(0) lgkmcnt(0)
	s_lshl_b32 s5, s20, 1
	ds_read2_b32 v[8:9], v28 offset0:33 offset1:41
	ds_read2_b32 v[10:11], v28 offset1:8
	ds_read2_b32 v[12:13], v28 offset0:66 offset1:74
	ds_read2_b32 v[14:15], v28 offset0:99 offset1:107
	ds_read2_b32 v[16:17], v28 offset0:132 offset1:140
	ds_read2_b32 v[18:19], v28 offset0:165 offset1:173
	ds_read2_b32 v[20:21], v28 offset0:198 offset1:206
	ds_read2_b32 v[22:23], v28 offset0:231 offset1:239
	s_add_u32 s6, s3, s5
	s_addc_u32 s7, s8, 0
	v_lshlrev_b32_e32 v210, 1, v2
	v_or_b32_e32 v66, s9, v27
	v_lshl_add_u64 v[4:5], s[6:7], 0, v[210:211]
	s_mov_b64 s[6:7], 0x2980000
	v_ashrrev_i32_e32 v67, 31, v66
	v_lshl_add_u64 v[64:65], v[4:5], 0, s[6:7]
	v_lshlrev_b64 v[66:67], 8, v[66:67]
	s_waitcnt lgkmcnt(6)
	v_cvt_pk_bf16_f32 v4, v10, v8
	s_waitcnt lgkmcnt(4)
	v_cvt_pk_bf16_f32 v5, v12, v14
	s_waitcnt lgkmcnt(2)
	v_cvt_pk_bf16_f32 v6, v16, v18
	s_waitcnt lgkmcnt(0)
	v_cvt_pk_bf16_f32 v7, v20, v22
	v_lshl_add_u64 v[66:67], v[64:65], 0, v[66:67]
	v_or_b32_e32 v8, s9, v29
	global_store_dwordx4 v[66:67], v[4:7], off
	s_nop 1
	v_cvt_pk_bf16_f32 v4, v11, v9
	v_ashrrev_i32_e32 v9, 31, v8
	v_cvt_pk_bf16_f32 v5, v13, v15
	v_cvt_pk_bf16_f32 v6, v17, v19
	v_cvt_pk_bf16_f32 v7, v21, v23
	v_lshlrev_b64 v[8:9], 8, v[8:9]
	ds_read2_b32 v[10:11], v28 offset0:49 offset1:57
	ds_read2_b32 v[12:13], v28 offset0:16 offset1:24
	ds_read2_b32 v[14:15], v28 offset0:82 offset1:90
	ds_read2_b32 v[16:17], v28 offset0:115 offset1:123
	ds_read2_b32 v[18:19], v28 offset0:148 offset1:156
	ds_read2_b32 v[20:21], v28 offset0:181 offset1:189
	ds_read2_b32 v[22:23], v28 offset0:214 offset1:222
	ds_read2_b32 v[66:67], v28 offset0:247 offset1:255
	v_lshl_add_u64 v[8:9], v[64:65], 0, v[8:9]
	global_store_dwordx4 v[8:9], v[4:7], off
	v_or_b32_e32 v8, s9, v30
	v_ashrrev_i32_e32 v9, 31, v8
	v_lshlrev_b64 v[8:9], 8, v[8:9]
	s_waitcnt lgkmcnt(6)
	v_cvt_pk_bf16_f32 v4, v12, v10
	s_waitcnt lgkmcnt(4)
	v_cvt_pk_bf16_f32 v5, v14, v16
	s_waitcnt lgkmcnt(2)
	v_cvt_pk_bf16_f32 v6, v18, v20
	s_waitcnt lgkmcnt(0)
	v_cvt_pk_bf16_f32 v7, v22, v66
	v_lshl_add_u64 v[8:9], v[64:65], 0, v[8:9]
	global_store_dwordx4 v[8:9], v[4:7], off
	v_or_b32_e32 v8, s9, v31
	v_ashrrev_i32_e32 v9, 31, v8
	v_lshlrev_b64 v[8:9], 8, v[8:9]
	v_cvt_pk_bf16_f32 v4, v13, v11
	v_cvt_pk_bf16_f32 v5, v15, v17
	v_cvt_pk_bf16_f32 v6, v19, v21
	v_cvt_pk_bf16_f32 v7, v23, v67
	v_lshl_add_u64 v[8:9], v[64:65], 0, v[8:9]
	global_store_dwordx4 v[8:9], v[4:7], off
	s_waitcnt lgkmcnt(0)

; __device__ __forceinline__ unsigned cvtpk(float lo, float hi) { f32x2_t v = {lo, hi}; bf16x2_t b = __builtin_convertvector(v, bf16x2_t); return __builtin_bit_cast(unsigned, b); }
; __device__ __forceinline__ void transpose_item(const float* W, int K, int N, bf16_t* WT, int mode, const float* kscale, float* scr, int item, int nblk, int lane) {
;     ...
;     for (int i = 0; i < 32; ++i) { const int kk = 2 * i + (lane >> 5); float v = wv[i]; if (kscale) v *= kscale[k0 + kk]; scr[kk * 33 + (lane & 31)] = v; }
;     __builtin_amdgcn_s_waitcnt(0); asm volatile("" ::: "memory");
;     const int c = lane & 7;
;     int drow0 = n0; if (mode == 1) drow0 = (n0 / 128) * 256 + (n0 % 128); else if (mode == 2) drow0 = (n0 / 128) * 256 + 128 + (n0 % 128);
; #pragma unroll
;     for (int j = 0; j < 4; ++j) { const int n = (lane >> 3) + 8 * j; const float* s = scr + (8 * c) * 33 + n;
;         u32x4 o; o.x = cvtpk(s[0 * 33], s[1 * 33]); o.y = cvtpk(s[2 * 33], s[3 * 33]); o.z = cvtpk(s[4 * 33], s[5 * 33]); o.w = cvtpk(s[6 * 33], s[7 * 33]);
;         *(u32x4*)(WT + (size_t)(drow0 + n) * K + k0 + 8 * c) = o; }
;     __builtin_amdgcn_s_waitcnt(0); asm volatile("" ::: "memory");
.LBB0_1088:
	s_mul_i32 s7, s4, 0x2900000
	s_mul_hi_i32 s6, s4, 0x2900000
	s_add_u32 s7, s78, s7
	s_addc_u32 s8, s79, s6
	ds_write_b32 v61, v6
	ds_write_b32 v62, v7
	s_waitcnt vmcnt(0) expcnt(0) lgkmcnt(0)
	s_lshl_b32 s5, s5, 1
	s_add_u32 s6, s7, s5
	ds_read2_b32 v[8:9], v28 offset0:33 offset1:41
	ds_read2_b32 v[10:11], v28 offset1:8
	ds_read2_b32 v[12:13], v28 offset0:66 offset1:74
	ds_read2_b32 v[14:15], v28 offset0:99 offset1:107
	ds_read2_b32 v[16:17], v28 offset0:132 offset1:140
	ds_read2_b32 v[18:19], v28 offset0:165 offset1:173
	ds_read2_b32 v[20:21], v28 offset0:198 offset1:206
	ds_read2_b32 v[22:23], v28 offset0:231 offset1:239
	s_addc_u32 s7, s8, 0
	v_lshlrev_b32_e32 v210, 1, v2
	v_lshl_add_u64 v[4:5], s[6:7], 0, v[210:211]
	s_mov_b64 s[6:7], 0x2900000
	v_lshl_add_u64 v[64:65], v[4:5], 0, s[6:7]
	s_waitcnt lgkmcnt(6)
	v_cvt_pk_bf16_f32 v4, v10, v8
	v_or_b32_e32 v8, s3, v27
	v_lshlrev_b32_e32 v210, 9, v8
	s_waitcnt lgkmcnt(4)
	v_cvt_pk_bf16_f32 v5, v12, v14
	s_waitcnt lgkmcnt(2)
	v_cvt_pk_bf16_f32 v6, v16, v18
	s_waitcnt lgkmcnt(0)
	v_cvt_pk_bf16_f32 v7, v20, v22
	v_lshl_add_u64 v[66:67], v[64:65], 0, v[210:211]
	global_store_dwordx4 v[66:67], v[4:7], off
	v_or_b32_e32 v8, s3, v29
	v_lshlrev_b32_e32 v210, 9, v8
	v_cvt_pk_bf16_f32 v4, v11, v9
	v_cvt_pk_bf16_f32 v5, v13, v15
	v_cvt_pk_bf16_f32 v6, v17, v19
	v_cvt_pk_bf16_f32 v7, v21, v23
	ds_read2_b32 v[10:11], v28 offset0:49 offset1:57
	ds_read2_b32 v[12:13], v28 offset0:16 offset1:24
	ds_read2_b32 v[14:15], v28 offset0:82 offset1:90
	ds_read2_b32 v[16:17], v28 offset0:115 offset1:123
	ds_read2_b32 v[18:19], v28 offset0:148 offset1:156
	ds_read2_b32 v[20:21], v28 offset0:181 offset1:189
	ds_read2_b32 v[22:23], v28 offset0:214 offset1:222
	ds_read2_b32 v[66:67], v28 offset0:247 offset1:255
	v_lshl_add_u64 v[8:9], v[64:65], 0, v[210:211]
	global_store_dwordx4 v[8:9], v[4:7], off
	v_or_b32_e32 v8, s3, v30
	v_lshlrev_b32_e32 v210, 9, v8
	s_waitcnt lgkmcnt(6)
	v_cvt_pk_bf16_f32 v4, v12, v10
	s_waitcnt lgkmcnt(4)
	v_cvt_pk_bf16_f32 v5, v14, v16
	s_waitcnt lgkmcnt(2)
	v_cvt_pk_bf16_f32 v6, v18, v20
	s_waitcnt lgkmcnt(0)
	v_cvt_pk_bf16_f32 v7, v22, v66
	v_lshl_add_u64 v[8:9], v[64:65], 0, v[210:211]
	global_store_dwordx4 v[8:9], v[4:7], off
	v_or_b32_e32 v8, s3, v31
	v_lshlrev_b32_e32 v210, 9, v8
	v_cvt_pk_bf16_f32 v4, v13, v11
	v_cvt_pk_bf16_f32 v5, v15, v17
	v_cvt_pk_bf16_f32 v6, v19, v21
	v_cvt_pk_bf16_f32 v7, v23, v67
	v_lshl_add_u64 v[8:9], v[64:65], 0, v[210:211]
	global_store_dwordx4 v[8:9], v[4:7], off
	s_waitcnt lgkmcnt(0)

; __device__ __forceinline__ unsigned cvtpk(float lo, float hi) { f32x2_t v = {lo, hi}; bf16x2_t b = __builtin_convertvector(v, bf16x2_t); return __builtin_bit_cast(unsigned, b); }
; __device__ __forceinline__ void transpose_item(const float* W, int K, int N, bf16_t* WT, int mode, const float* kscale, float* scr, int item, int nblk, int lane) {
;     ...
;     for (int i = 0; i < 32; ++i) { const int kk = 2 * i + (lane >> 5); float v = wv[i]; if (kscale) v *= kscale[k0 + kk]; scr[kk * 33 + (lane & 31)] = v; }
;     __builtin_amdgcn_s_waitcnt(0); asm volatile("" ::: "memory");
;     const int c = lane & 7;
;     int drow0 = n0; if (mode == 1) drow0 = (n0 / 128) * 256 + (n0 % 128); else if (mode == 2) drow0 = (n0 / 128) * 256 + 128 + (n0 % 128);
; #pragma unroll
;     for (int j = 0; j < 4; ++j) { const int n = (lane >> 3) + 8 * j; const float* s = scr + (8 * c) * 33 + n;
;         u32x4 o; o.x = cvtpk(s[0 * 33], s[1 * 33]); o.y = cvtpk(s[2 * 33], s[3 * 33]); o.z = cvtpk(s[4 * 33], s[5 * 33]); o.w = cvtpk(s[6 * 33], s[7 * 33]);
;         *(u32x4*)(WT + (size_t)(drow0 + n) * K + k0 + 8 * c) = o; }
;     __builtin_amdgcn_s_waitcnt(0); asm volatile("" ::: "memory");
.LBB0_1179:
	s_mul_i32 s6, s4, 0x2900000
	s_mul_hi_i32 s5, s4, 0x2900000
	s_add_u32 s6, s78, s6
	s_addc_u32 s5, s79, s5
	ds_write_b32 v61, v4
	ds_write_b32 v62, v5
	s_waitcnt vmcnt(0) expcnt(0) lgkmcnt(0)
	s_lshl_b32 s7, s8, 1
	s_add_u32 s6, s6, s7
	ds_read2_b32 v[8:9], v28 offset0:33 offset1:41
	ds_read2_b32 v[10:11], v28 offset1:8
	ds_read2_b32 v[12:13], v28 offset0:66 offset1:74
	ds_read2_b32 v[14:15], v28 offset0:99 offset1:107
	ds_read2_b32 v[16:17], v28 offset0:132 offset1:140
	ds_read2_b32 v[18:19], v28 offset0:165 offset1:173
	ds_read2_b32 v[20:21], v28 offset0:198 offset1:206
	ds_read2_b32 v[22:23], v28 offset0:231 offset1:239
	s_addc_u32 s7, s5, 0
	v_lshlrev_b32_e32 v210, 1, v2
	v_lshl_add_u64 v[4:5], s[6:7], 0, v[210:211]
	s_mov_b64 s[6:7], 0x2300000
	v_lshl_add_u64 v[64:65], v[4:5], 0, s[6:7]
	s_waitcnt lgkmcnt(6)
	v_cvt_pk_bf16_f32 v4, v10, v8
	v_or_b32_e32 v8, s3, v27
	v_lshlrev_b32_e32 v210, 11, v8
	s_waitcnt lgkmcnt(4)
	v_cvt_pk_bf16_f32 v5, v12, v14
	s_waitcnt lgkmcnt(2)
	v_cvt_pk_bf16_f32 v6, v16, v18
	s_waitcnt lgkmcnt(0)
	v_cvt_pk_bf16_f32 v7, v20, v22
	v_lshl_add_u64 v[66:67], v[64:65], 0, v[210:211]
	global_store_dwordx4 v[66:67], v[4:7], off
	v_or_b32_e32 v8, s3, v29
	v_lshlrev_b32_e32 v210, 11, v8
	v_cvt_pk_bf16_f32 v4, v11, v9
	v_cvt_pk_bf16_f32 v5, v13, v15
	v_cvt_pk_bf16_f32 v6, v17, v19
	v_cvt_pk_bf16_f32 v7, v21, v23
	ds_read2_b32 v[10:11], v28 offset0:49 offset1:57
	ds_read2_b32 v[12:13], v28 offset0:16 offset1:24
	ds_read2_b32 v[14:15], v28 offset0:82 offset1:90
	ds_read2_b32 v[16:17], v28 offset0:115 offset1:123
	ds_read2_b32 v[18:19], v28 offset0:148 offset1:156
	ds_read2_b32 v[20:21], v28 offset0:181 offset1:189
	ds_read2_b32 v[22:23], v28 offset0:214 offset1:222
	ds_read2_b32 v[66:67], v28 offset0:247 offset1:255
	v_lshl_add_u64 v[8:9], v[64:65], 0, v[210:211]
	global_store_dwordx4 v[8:9], v[4:7], off
	v_or_b32_e32 v8, s3, v30
	v_lshlrev_b32_e32 v210, 11, v8
	s_waitcnt lgkmcnt(6)
	v_cvt_pk_bf16_f32 v4, v12, v10
	s_waitcnt lgkmcnt(4)
	v_cvt_pk_bf16_f32 v5, v14, v16
	s_waitcnt lgkmcnt(2)
	v_cvt_pk_bf16_f32 v6, v18, v20
	s_waitcnt lgkmcnt(0)
	v_cvt_pk_bf16_f32 v7, v22, v66
	v_lshl_add_u64 v[8:9], v[64:65], 0, v[210:211]
	global_store_dwordx4 v[8:9], v[4:7], off
	v_or_b32_e32 v8, s3, v31
	v_lshlrev_b32_e32 v210, 11, v8
	v_cvt_pk_bf16_f32 v4, v13, v11
	v_cvt_pk_bf16_f32 v5, v15, v17
	v_cvt_pk_bf16_f32 v6, v19, v21
	v_cvt_pk_bf16_f32 v7, v23, v67
	v_lshl_add_u64 v[8:9], v[64:65], 0, v[210:211]
	global_store_dwordx4 v[8:9], v[4:7], off
	s_waitcnt lgkmcnt(0)

; __device__ __forceinline__ void transpose_item(const float* W, int K, int N, bf16_t* WT, int mode, const float* kscale, float* scr, int item, int nblk, int lane) {
;     const int kb = item / nblk, nb = item % nblk, k0 = 64 * kb, n0 = 32 * nb;
;     const int nn = n0 + (lane & 31);
;     float wv[32];
; #pragma unroll
;     for (int i = 0; i < 32; ++i) { const int kk = 2 * i + (lane >> 5); wv[i] = (nn < N) ? W[(size_t)(k0 + kk) * N + nn] : 0.f; }
; __global__ void __launch_bounds__(NWAVES * 64, 2) mega_fwd(Args args) {
;     ...
;                 if (r < I_D) { transpose_item(INF(23, l, D * FF), FF, D, WPTR(l, WL_D2), 0, nullptr, scr, r, 32, c.lane); continue; } r -= I_D;
.LBB0_1181:
	s_andn2_b64 vcc, exec, s[6:7]
	s_cbranch_vccnz .LBB0_1183
	s_load_dwordx2 s[6:7], s[0:1], 0xb8
	s_mul_i32 s5, s4, 0xb00000
	s_mul_hi_i32 s3, s4, 0xb00000
	s_mul_i32 s11, s4, 0x2900000
	s_mul_hi_i32 s10, s4, 0x2900000
	s_waitcnt lgkmcnt(0)
	s_add_u32 s8, s6, s5
	s_addc_u32 s9, s7, s3
	s_add_u32 s5, s78, s11
	s_mul_i32 s3, s4, 0xffffb0c0
	s_addc_u32 s6, s79, s10
	s_add_i32 s3, s31, s3
	s_addk_i32 s3, 0xdf00
	s_and_b32 s7, s3, 0x1ffc0
	s_and_b32 s3, s27, 0x3e0
	v_or_b32_e32 v4, s3, v25
	v_or_b32_e32 v6, s7, v0
	v_lshlrev_b32_e32 v210, 2, v4
	v_lshl_add_u64 v[4:5], s[8:9], 0, v[210:211]
	v_lshlrev_b32_e32 v210, 12, v6
	v_lshl_add_u64 v[4:5], v[4:5], 0, v[210:211]
	s_movk_i32 s8, 0x2000
	v_add_co_u32_e32 v6, vcc, s8, v4
	s_movk_i32 s8, 0x4000
	s_nop 0
	v_addc_co_u32_e32 v7, vcc, 0, v5, vcc
	v_add_co_u32_e32 v8, vcc, s8, v4
	s_movk_i32 s8, 0x6000
	s_nop 0
	v_addc_co_u32_e32 v9, vcc, 0, v5, vcc
	v_add_co_u32_e32 v10, vcc, s8, v4
	s_mov_b32 s8, 0x8000
	s_nop 0
	v_addc_co_u32_e32 v11, vcc, 0, v5, vcc
	v_add_co_u32_e32 v12, vcc, s8, v4
	s_mov_b32 s8, 0xa000
	s_nop 0
	v_addc_co_u32_e32 v13, vcc, 0, v5, vcc
	v_add_co_u32_e32 v14, vcc, s8, v4
	s_mov_b32 s8, 0xc000
	s_nop 0
	v_addc_co_u32_e32 v15, vcc, 0, v5, vcc
	v_add_co_u32_e32 v16, vcc, s8, v4
	s_mov_b32 s8, 0xe000
	s_nop 0
	v_addc_co_u32_e32 v17, vcc, 0, v5, vcc
	v_add_co_u32_e32 v18, vcc, s8, v4
	s_mov_b32 s8, 0x12000
	s_nop 0
	v_addc_co_u32_e32 v19, vcc, 0, v5, vcc
	global_load_dword v22, v[4:5], off
	global_load_dword v23, v[6:7], off
	global_load_dword v63, v[8:9], off
	global_load_dword v64, v[10:11], off
	global_load_dword v65, v[12:13], off
	global_load_dword v66, v[14:15], off
	global_load_dword v67, v[16:17], off
	global_load_dword v68, v[18:19], off
	v_add_co_u32_e32 v6, vcc, s89, v4
	s_lshl_b32 s7, s7, 1
	s_nop 0
	v_addc_co_u32_e32 v7, vcc, 0, v5, vcc
	v_add_co_u32_e32 v8, vcc, s8, v4
	s_mov_b32 s8, 0x14000
	s_nop 0
	v_addc_co_u32_e32 v9, vcc, 0, v5, vcc
	v_add_co_u32_e32 v10, vcc, s8, v4
	s_mov_b32 s8, 0x18000
	s_nop 0
	v_addc_co_u32_e32 v11, vcc, 0, v5, vcc
	v_add_co_u32_e32 v12, vcc, s90, v4
	v_lshlrev_b32_e32 v210, 1, v2
	s_nop 0
	v_addc_co_u32_e32 v13, vcc, 0, v5, vcc
	v_add_co_u32_e32 v14, vcc, s8, v4
	s_mov_b32 s8, 0x1a000
	s_nop 0
	v_addc_co_u32_e32 v15, vcc, 0, v5, vcc
	v_add_co_u32_e32 v16, vcc, s8, v4
	s_mov_b32 s8, 0x1c000
	s_nop 0
	v_addc_co_u32_e32 v17, vcc, 0, v5, vcc
	v_add_co_u32_e32 v18, vcc, s8, v4
	s_mov_b32 s8, 0x1e000
	s_nop 0
	v_addc_co_u32_e32 v19, vcc, 0, v5, vcc
	v_add_co_u32_e32 v20, vcc, s8, v4
	s_mov_b32 s8, 0x20000
	s_nop 0
	v_addc_co_u32_e32 v21, vcc, 0, v5, vcc
	global_load_dword v69, v[6:7], off
	global_load_dword v70, v[8:9], off
	global_load_dword v71, v[10:11], off
	global_load_dword v72, v[12:13], off
	global_load_dword v73, v[14:15], off
	global_load_dword v74, v[16:17], off
	global_load_dword v75, v[18:19], off
	global_load_dword v76, v[20:21], off
	v_add_co_u32_e32 v6, vcc, s8, v4
	s_mov_b32 s8, 0x22000
	s_nop 0
	v_addc_co_u32_e32 v7, vcc, 0, v5, vcc
	v_add_co_u32_e32 v8, vcc, s8, v4
	s_mov_b32 s8, 0x24000
	s_nop 0
	v_addc_co_u32_e32 v9, vcc, 0, v5, vcc
	v_add_co_u32_e32 v10, vcc, s8, v4
	s_mov_b32 s8, 0x26000
	s_nop 0
	v_addc_co_u32_e32 v11, vcc, 0, v5, vcc
	v_add_co_u32_e32 v12, vcc, s8, v4
	s_mov_b32 s8, 0x28000
	s_nop 0
	v_addc_co_u32_e32 v13, vcc, 0, v5, vcc
	v_add_co_u32_e32 v14, vcc, s8, v4
	s_mov_b32 s8, 0x2a000
	s_nop 0
	v_addc_co_u32_e32 v15, vcc, 0, v5, vcc
	v_add_co_u32_e32 v16, vcc, s8, v4
	s_mov_b32 s8, 0x2c000
	s_nop 0
	v_addc_co_u32_e32 v17, vcc, 0, v5, vcc
	v_add_co_u32_e32 v18, vcc, s8, v4
	s_mov_b32 s8, 0x2e000
	s_nop 0
	v_addc_co_u32_e32 v19, vcc, 0, v5, vcc
	v_add_co_u32_e32 v20, vcc, s8, v4
	s_mov_b32 s8, 0x30000
	s_nop 0
	v_addc_co_u32_e32 v21, vcc, 0, v5, vcc
	global_load_dword v77, v[6:7], off
	global_load_dword v78, v[8:9], off
	global_load_dword v79, v[10:11], off
	global_load_dword v80, v[12:13], off
	global_load_dword v81, v[14:15], off
	global_load_dword v82, v[16:17], off
	global_load_dword v83, v[18:19], off
	s_nop 0
	global_load_dword v20, v[20:21], off
	v_add_co_u32_e32 v6, vcc, s8, v4
	s_mov_b32 s8, 0x32000
	s_nop 0
	v_addc_co_u32_e32 v7, vcc, 0, v5, vcc
	v_add_co_u32_e32 v8, vcc, s8, v4
	s_mov_b32 s8, 0x34000
	s_nop 0
	v_addc_co_u32_e32 v9, vcc, 0, v5, vcc
	v_add_co_u32_e32 v10, vcc, s8, v4
	s_mov_b32 s8, 0x36000
	s_nop 0
	v_addc_co_u32_e32 v11, vcc, 0, v5, vcc
	v_add_co_u32_e32 v12, vcc, s8, v4
	s_mov_b32 s8, 0x38000
	s_nop 0
	v_addc_co_u32_e32 v13, vcc, 0, v5, vcc
	v_add_co_u32_e32 v14, vcc, s8, v4
	s_mov_b32 s8, 0x3a000
	s_nop 0
	v_addc_co_u32_e32 v15, vcc, 0, v5, vcc
	v_add_co_u32_e32 v16, vcc, s8, v4
	s_mov_b32 s8, 0x3c000
	s_nop 0
	v_addc_co_u32_e32 v17, vcc, 0, v5, vcc
	v_add_co_u32_e32 v18, vcc, s8, v4
	s_mov_b32 s8, 0x3e000
	s_nop 0
	v_addc_co_u32_e32 v19, vcc, 0, v5, vcc
	v_add_co_u32_e32 v4, vcc, s8, v4
	s_add_u32 s8, s5, s7
	s_nop 0
	v_addc_co_u32_e32 v5, vcc, 0, v5, vcc
	global_load_dword v6, v[6:7], off
	s_nop 0
	global_load_dword v7, v[8:9], off
	s_nop 0
	global_load_dword v8, v[10:11], off
	global_load_dword v9, v[12:13], off
	s_nop 0
	global_load_dword v10, v[14:15], off
	global_load_dword v11, v[16:17], off
	global_load_dword v12, v[18:19], off
	s_nop 0
	global_load_dword v4, v[4:5], off
	v_add_u32_e32 v5, 0x400, v26
	s_waitcnt vmcnt(30)
; __device__ __forceinline__ unsigned cvtpk(float lo, float hi) { f32x2_t v = {lo, hi}; bf16x2_t b = __builtin_convertvector(v, bf16x2_t); return __builtin_bit_cast(unsigned, b); }
; __device__ __forceinline__ void transpose_item(const float* W, int K, int N, bf16_t* WT, int mode, const float* kscale, float* scr, int item, int nblk, int lane) {
;     ...
;     for (int i = 0; i < 32; ++i) { const int kk = 2 * i + (lane >> 5); float v = wv[i]; if (kscale) v *= kscale[k0 + kk]; scr[kk * 33 + (lane & 31)] = v; }
;     __builtin_amdgcn_s_waitcnt(0); asm volatile("" ::: "memory");
;     const int c = lane & 7;
;     int drow0 = n0; if (mode == 1) drow0 = (n0 / 128) * 256 + (n0 % 128); else if (mode == 2) drow0 = (n0 / 128) * 256 + 128 + (n0 % 128);
; #pragma unroll
;     for (int j = 0; j < 4; ++j) { const int n = (lane >> 3) + 8 * j; const float* s = scr + (8 * c) * 33 + n;
;         u32x4 o; o.x = cvtpk(s[0 * 33], s[1 * 33]); o.y = cvtpk(s[2 * 33], s[3 * 33]); o.z = cvtpk(s[4 * 33], s[5 * 33]); o.w = cvtpk(s[6 * 33], s[7 * 33]);
;         *(u32x4*)(WT + (size_t)(drow0 + n) * K + k0 + 8 * c) = o; }
;     __builtin_amdgcn_s_waitcnt(0); asm volatile("" ::: "memory");
	ds_write2_b32 v26, v22, v23 offset1:66
	s_waitcnt vmcnt(28)
	ds_write2_b32 v26, v63, v64 offset0:132 offset1:198
	s_waitcnt vmcnt(26)
	ds_write2_b32 v5, v65, v66 offset0:8 offset1:74
	s_waitcnt vmcnt(24)
	ds_write2_b32 v5, v67, v68 offset0:140 offset1:206
	v_add_u32_e32 v5, 0x800, v26
	s_waitcnt vmcnt(22)
	ds_write2_b32 v5, v69, v70 offset0:16 offset1:82
	s_waitcnt vmcnt(20)
	ds_write2_b32 v5, v71, v72 offset0:148 offset1:214
	v_add_u32_e32 v5, 0xc00, v26
	s_waitcnt vmcnt(18)
	ds_write2_b32 v5, v73, v74 offset0:24 offset1:90
	s_waitcnt vmcnt(16)
	ds_write2_b32 v5, v75, v76 offset0:156 offset1:222
	v_add_u32_e32 v5, 0x1000, v26
	s_waitcnt vmcnt(14)
	ds_write2_b32 v5, v77, v78 offset0:32 offset1:98
	s_waitcnt vmcnt(12)
	ds_write2_b32 v5, v79, v80 offset0:164 offset1:230
	v_add_u32_e32 v5, 0x1400, v26
	s_waitcnt vmcnt(10)
	ds_write2_b32 v5, v81, v82 offset0:40 offset1:106
	s_waitcnt vmcnt(8)
	ds_write2_b32 v5, v83, v20 offset0:172 offset1:238
	v_add_u32_e32 v5, 0x1800, v26
	s_waitcnt vmcnt(6)
	ds_write2_b32 v5, v6, v7 offset0:48 offset1:114
	s_waitcnt vmcnt(4)
	ds_write2_b32 v5, v8, v9 offset0:180 offset1:246
	v_add_u32_e32 v5, 0x1c00, v26
	s_waitcnt vmcnt(2)
	ds_write2_b32 v5, v10, v11 offset0:56 offset1:122
	s_waitcnt vmcnt(0)
	ds_write2_b32 v5, v12, v4 offset0:188 offset1:254
	s_waitcnt vmcnt(0) expcnt(0) lgkmcnt(0)
	s_addc_u32 s9, s6, 0
	ds_read2_b32 v[8:9], v28 offset0:33 offset1:41
	ds_read2_b32 v[10:11], v28 offset1:8
	ds_read2_b32 v[12:13], v28 offset0:66 offset1:74
	ds_read2_b32 v[14:15], v28 offset0:99 offset1:107
	ds_read2_b32 v[16:17], v28 offset0:132 offset1:140
	ds_read2_b32 v[18:19], v28 offset0:165 offset1:173
	ds_read2_b32 v[20:21], v28 offset0:198 offset1:206
	ds_read2_b32 v[22:23], v28 offset0:231 offset1:239
	v_lshl_add_u64 v[4:5], s[8:9], 0, v[210:211]
	s_mov_b64 s[6:7], 0x1d00000
	v_lshl_add_u64 v[64:65], v[4:5], 0, s[6:7]
	s_waitcnt lgkmcnt(6)
	v_cvt_pk_bf16_f32 v4, v10, v8
	v_or_b32_e32 v8, s3, v27
	v_mul_u32_u24_e32 v8, 0xb00, v8
	v_lshlrev_b32_e32 v210, 1, v8
	s_waitcnt lgkmcnt(4)
	v_cvt_pk_bf16_f32 v5, v12, v14
	s_waitcnt lgkmcnt(2)
	v_cvt_pk_bf16_f32 v6, v16, v18
	s_waitcnt lgkmcnt(0)
	v_cvt_pk_bf16_f32 v7, v20, v22
	v_lshl_add_u64 v[66:67], v[64:65], 0, v[210:211]
	v_or_b32_e32 v8, s3, v29
	global_store_dwordx4 v[66:67], v[4:7], off
	v_mul_u32_u24_e32 v8, 0xb00, v8
	v_lshlrev_b32_e32 v210, 1, v8
	v_cvt_pk_bf16_f32 v4, v11, v9
	v_cvt_pk_bf16_f32 v5, v13, v15
	v_cvt_pk_bf16_f32 v6, v17, v19
	v_cvt_pk_bf16_f32 v7, v21, v23
	ds_read2_b32 v[10:11], v28 offset0:16 offset1:24
	ds_read2_b32 v[12:13], v28 offset0:49 offset1:57
	ds_read2_b32 v[14:15], v28 offset0:82 offset1:90
	ds_read2_b32 v[16:17], v28 offset0:115 offset1:123
	ds_read2_b32 v[18:19], v28 offset0:148 offset1:156
	ds_read2_b32 v[20:21], v28 offset0:181 offset1:189
	ds_read2_b32 v[22:23], v28 offset0:214 offset1:222
	ds_read2_b32 v[66:67], v28 offset0:247 offset1:255
	v_lshl_add_u64 v[8:9], v[64:65], 0, v[210:211]
	global_store_dwordx4 v[8:9], v[4:7], off
	v_or_b32_e32 v8, s3, v30
	v_mul_u32_u24_e32 v8, 0xb00, v8
	v_lshlrev_b32_e32 v210, 1, v8
	s_waitcnt lgkmcnt(6)
	v_cvt_pk_bf16_f32 v4, v10, v12
	s_waitcnt lgkmcnt(4)
	v_cvt_pk_bf16_f32 v5, v14, v16
	s_waitcnt lgkmcnt(2)
	v_cvt_pk_bf16_f32 v6, v18, v20
	s_waitcnt lgkmcnt(0)
	v_cvt_pk_bf16_f32 v7, v22, v66
	v_lshl_add_u64 v[8:9], v[64:65], 0, v[210:211]
	global_store_dwordx4 v[8:9], v[4:7], off
	v_or_b32_e32 v8, s3, v31
	v_mul_u32_u24_e32 v8, 0xb00, v8
	v_lshlrev_b32_e32 v210, 1, v8
	v_cvt_pk_bf16_f32 v4, v11, v13
	v_cvt_pk_bf16_f32 v5, v15, v17
	v_cvt_pk_bf16_f32 v6, v19, v21
	v_cvt_pk_bf16_f32 v7, v23, v67
	v_lshl_add_u64 v[8:9], v[64:65], 0, v[210:211]
	global_store_dwordx4 v[8:9], v[4:7], off
	s_waitcnt lgkmcnt(0)

; __device__ __forceinline__ unsigned cvtpk(float lo, float hi) { f32x2_t v = {lo, hi}; bf16x2_t b = __builtin_convertvector(v, bf16x2_t); return __builtin_bit_cast(unsigned, b); }
; __device__ __forceinline__ void transpose_item(const float* W, int K, int N, bf16_t* WT, int mode, const float* kscale, float* scr, int item, int nblk, int lane) {
;     ...
;     for (int i = 0; i < 32; ++i) { const int kk = 2 * i + (lane >> 5); float v = wv[i]; if (kscale) v *= kscale[k0 + kk]; scr[kk * 33 + (lane & 31)] = v; }
;     __builtin_amdgcn_s_waitcnt(0); asm volatile("" ::: "memory");
;     const int c = lane & 7;
;     int drow0 = n0; if (mode == 1) drow0 = (n0 / 128) * 256 + (n0 % 128); else if (mode == 2) drow0 = (n0 / 128) * 256 + 128 + (n0 % 128);
; #pragma unroll
;     for (int j = 0; j < 4; ++j) { const int n = (lane >> 3) + 8 * j; const float* s = scr + (8 * c) * 33 + n;
;         u32x4 o; o.x = cvtpk(s[0 * 33], s[1 * 33]); o.y = cvtpk(s[2 * 33], s[3 * 33]); o.z = cvtpk(s[4 * 33], s[5 * 33]); o.w = cvtpk(s[6 * 33], s[7 * 33]);
;         *(u32x4*)(WT + (size_t)(drow0 + n) * K + k0 + 8 * c) = o; }
;     __builtin_amdgcn_s_waitcnt(0); asm volatile("" ::: "memory");
.LBB0_1209:
	s_mul_i32 s7, s4, 0x2900000
	s_mul_hi_i32 s6, s4, 0x2900000
	s_add_u32 s7, s78, s7
	s_addc_u32 s9, s79, s6
	s_lshl_b32 s5, s5, 6
	s_and_b32 s5, s5, 0x1f00
	s_and_b32 s6, s8, 0x60
	s_or_b32 s5, s6, s5
	s_bitset1_b32 s5, 7
	ds_write_b32 v61, v6
	ds_write_b32 v62, v7
	s_waitcnt vmcnt(0) expcnt(0) lgkmcnt(0)
	s_and_b32 s5, s5, 0x1fe0
	s_lshl_b32 s3, s3, 1
	s_add_u32 s6, s7, s3
	ds_read2_b32 v[8:9], v28 offset0:33 offset1:41
	ds_read2_b32 v[10:11], v28 offset1:8
	ds_read2_b32 v[12:13], v28 offset0:66 offset1:74
	ds_read2_b32 v[14:15], v28 offset0:99 offset1:107
	ds_read2_b32 v[16:17], v28 offset0:132 offset1:140
	ds_read2_b32 v[18:19], v28 offset0:165 offset1:173
	ds_read2_b32 v[20:21], v28 offset0:198 offset1:206
	ds_read2_b32 v[22:23], v28 offset0:231 offset1:239
	s_addc_u32 s7, s9, 0
	v_lshlrev_b32_e32 v210, 1, v2
	v_lshl_add_u64 v[4:5], s[6:7], 0, v[210:211]
	s_mov_b64 s[6:7], 0x1200000
	v_lshl_add_u64 v[64:65], v[4:5], 0, s[6:7]
	s_waitcnt lgkmcnt(6)
	v_cvt_pk_bf16_f32 v4, v10, v8
	v_or_b32_e32 v8, s5, v27
	v_lshlrev_b32_e32 v210, 11, v8
	s_waitcnt lgkmcnt(4)
	v_cvt_pk_bf16_f32 v5, v12, v14
	s_waitcnt lgkmcnt(2)
	v_cvt_pk_bf16_f32 v6, v16, v18
	s_waitcnt lgkmcnt(0)
	v_cvt_pk_bf16_f32 v7, v20, v22
	v_lshl_add_u64 v[66:67], v[64:65], 0, v[210:211]
	global_store_dwordx4 v[66:67], v[4:7], off
	v_or_b32_e32 v8, s5, v29
	v_lshlrev_b32_e32 v210, 11, v8
	v_cvt_pk_bf16_f32 v4, v11, v9
	v_cvt_pk_bf16_f32 v5, v13, v15
	v_cvt_pk_bf16_f32 v6, v17, v19
	v_cvt_pk_bf16_f32 v7, v21, v23
	ds_read2_b32 v[10:11], v28 offset0:49 offset1:57
	ds_read2_b32 v[12:13], v28 offset0:16 offset1:24
	ds_read2_b32 v[14:15], v28 offset0:82 offset1:90
	ds_read2_b32 v[16:17], v28 offset0:115 offset1:123
	ds_read2_b32 v[18:19], v28 offset0:148 offset1:156
	ds_read2_b32 v[20:21], v28 offset0:181 offset1:189
	ds_read2_b32 v[22:23], v28 offset0:214 offset1:222
	ds_read2_b32 v[66:67], v28 offset0:247 offset1:255
	v_lshl_add_u64 v[8:9], v[64:65], 0, v[210:211]
	global_store_dwordx4 v[8:9], v[4:7], off
	v_or_b32_e32 v8, s5, v30
	v_lshlrev_b32_e32 v210, 11, v8
	s_waitcnt lgkmcnt(6)
	v_cvt_pk_bf16_f32 v4, v12, v10
	s_waitcnt lgkmcnt(4)
	v_cvt_pk_bf16_f32 v5, v14, v16
	s_waitcnt lgkmcnt(2)
	v_cvt_pk_bf16_f32 v6, v18, v20
	s_waitcnt lgkmcnt(0)
	v_cvt_pk_bf16_f32 v7, v22, v66
	v_lshl_add_u64 v[8:9], v[64:65], 0, v[210:211]
	global_store_dwordx4 v[8:9], v[4:7], off
	v_or_b32_e32 v8, s5, v31
	v_lshlrev_b32_e32 v210, 11, v8
	v_cvt_pk_bf16_f32 v4, v13, v11
	v_cvt_pk_bf16_f32 v5, v15, v17
	v_cvt_pk_bf16_f32 v6, v19, v21
	v_cvt_pk_bf16_f32 v7, v23, v67
	v_lshl_add_u64 v[8:9], v[64:65], 0, v[210:211]
	global_store_dwordx4 v[8:9], v[4:7], off
	s_waitcnt lgkmcnt(0)

; __device__ __forceinline__ unsigned cvtpk(float lo, float hi) { f32x2_t v = {lo, hi}; bf16x2_t b = __builtin_convertvector(v, bf16x2_t); return __builtin_bit_cast(unsigned, b); }
; __device__ __forceinline__ void transpose_item(const float* W, int K, int N, bf16_t* WT, int mode, const float* kscale, float* scr, int item, int nblk, int lane) {
;     ...
;     for (int i = 0; i < 32; ++i) { const int kk = 2 * i + (lane >> 5); float v = wv[i]; if (kscale) v *= kscale[k0 + kk]; scr[kk * 33 + (lane & 31)] = v; }
;     __builtin_amdgcn_s_waitcnt(0); asm volatile("" ::: "memory");
;     const int c = lane & 7;
;     int drow0 = n0; if (mode == 1) drow0 = (n0 / 128) * 256 + (n0 % 128); else if (mode == 2) drow0 = (n0 / 128) * 256 + 128 + (n0 % 128);
; #pragma unroll
;     for (int j = 0; j < 4; ++j) { const int n = (lane >> 3) + 8 * j; const float* s = scr + (8 * c) * 33 + n;
;         u32x4 o; o.x = cvtpk(s[0 * 33], s[1 * 33]); o.y = cvtpk(s[2 * 33], s[3 * 33]); o.z = cvtpk(s[4 * 33], s[5 * 33]); o.w = cvtpk(s[6 * 33], s[7 * 33]);
;         *(u32x4*)(WT + (size_t)(drow0 + n) * K + k0 + 8 * c) = o; }
;     __builtin_amdgcn_s_waitcnt(0); asm volatile("" ::: "memory");
.LBB0_1236:
	s_mul_i32 s7, s4, 0x2900000
	s_mul_hi_i32 s6, s4, 0x2900000
	s_add_u32 s7, s78, s7
	s_addc_u32 s9, s79, s6
	s_lshl_b32 s5, s5, 6
	s_and_b32 s5, s5, 0x1f00
	s_and_b32 s6, s8, 0x60
	s_or_b32 s5, s5, s6
	ds_write_b32 v61, v6
	ds_write_b32 v62, v7
	s_waitcnt vmcnt(0) expcnt(0) lgkmcnt(0)
	s_and_b32 s5, s5, 0x1f60
	s_lshl_b32 s3, s3, 1
	s_add_u32 s6, s7, s3
	ds_read2_b32 v[8:9], v28 offset0:33 offset1:41
	ds_read2_b32 v[10:11], v28 offset1:8
	ds_read2_b32 v[12:13], v28 offset0:66 offset1:74
	ds_read2_b32 v[14:15], v28 offset0:99 offset1:107
	ds_read2_b32 v[16:17], v28 offset0:132 offset1:140
	ds_read2_b32 v[18:19], v28 offset0:165 offset1:173
	ds_read2_b32 v[20:21], v28 offset0:198 offset1:206
	ds_read2_b32 v[22:23], v28 offset0:231 offset1:239
	s_addc_u32 s7, s9, 0
	v_lshlrev_b32_e32 v210, 1, v2
	v_lshl_add_u64 v[4:5], s[6:7], 0, v[210:211]
	s_mov_b64 s[6:7], 0x1200000
	v_lshl_add_u64 v[64:65], v[4:5], 0, s[6:7]
	s_waitcnt lgkmcnt(6)
	v_cvt_pk_bf16_f32 v4, v10, v8
	v_or_b32_e32 v8, s5, v27
	v_lshlrev_b32_e32 v210, 11, v8
	s_waitcnt lgkmcnt(4)
	v_cvt_pk_bf16_f32 v5, v12, v14
	s_waitcnt lgkmcnt(2)
	v_cvt_pk_bf16_f32 v6, v16, v18
	s_waitcnt lgkmcnt(0)
	v_cvt_pk_bf16_f32 v7, v20, v22
	v_lshl_add_u64 v[66:67], v[64:65], 0, v[210:211]
	global_store_dwordx4 v[66:67], v[4:7], off
	v_or_b32_e32 v8, s5, v29
	v_lshlrev_b32_e32 v210, 11, v8
	v_cvt_pk_bf16_f32 v4, v11, v9
	v_cvt_pk_bf16_f32 v5, v13, v15
	v_cvt_pk_bf16_f32 v6, v17, v19
	v_cvt_pk_bf16_f32 v7, v21, v23
	ds_read2_b32 v[10:11], v28 offset0:49 offset1:57
	ds_read2_b32 v[12:13], v28 offset0:16 offset1:24
	ds_read2_b32 v[14:15], v28 offset0:82 offset1:90
	ds_read2_b32 v[16:17], v28 offset0:115 offset1:123
	ds_read2_b32 v[18:19], v28 offset0:148 offset1:156
	ds_read2_b32 v[20:21], v28 offset0:181 offset1:189
	ds_read2_b32 v[22:23], v28 offset0:214 offset1:222
	ds_read2_b32 v[66:67], v28 offset0:247 offset1:255
	v_lshl_add_u64 v[8:9], v[64:65], 0, v[210:211]
	global_store_dwordx4 v[8:9], v[4:7], off
	v_or_b32_e32 v8, s5, v30
	v_lshlrev_b32_e32 v210, 11, v8
	s_waitcnt lgkmcnt(6)
	v_cvt_pk_bf16_f32 v4, v12, v10
	s_waitcnt lgkmcnt(4)
	v_cvt_pk_bf16_f32 v5, v14, v16
	s_waitcnt lgkmcnt(2)
	v_cvt_pk_bf16_f32 v6, v18, v20
	s_waitcnt lgkmcnt(0)
	v_cvt_pk_bf16_f32 v7, v22, v66
	v_lshl_add_u64 v[8:9], v[64:65], 0, v[210:211]
	global_store_dwordx4 v[8:9], v[4:7], off
	v_or_b32_e32 v8, s5, v31
	v_lshlrev_b32_e32 v210, 11, v8
	v_cvt_pk_bf16_f32 v4, v13, v11
	v_cvt_pk_bf16_f32 v5, v15, v17
	v_cvt_pk_bf16_f32 v6, v19, v21
	v_cvt_pk_bf16_f32 v7, v23, v67
	v_lshl_add_u64 v[8:9], v[64:65], 0, v[210:211]
	global_store_dwordx4 v[8:9], v[4:7], off
	s_waitcnt lgkmcnt(0)

; __device__ __forceinline__ void transpose_item(const float* W, int K, int N, bf16_t* WT, int mode, const float* kscale, float* scr, int item, int nblk, int lane) {
;     const int kb = item / nblk, nb = item % nblk, k0 = 64 * kb, n0 = 32 * nb;
;     const int nn = n0 + (lane & 31);
;     float wv[32];
; #pragma unroll
;     for (int i = 0; i < 32; ++i) { const int kk = 2 * i + (lane >> 5); wv[i] = (nn < N) ? W[(size_t)(k0 + kk) * N + nn] : 0.f; }
; __global__ void __launch_bounds__(NWAVES * 64, 2) mega_fwd(Args args) {
;     ...
;                 if (r < I_D) { transpose_item(INF(6, l, D * FF), FF, D, WPTR(l, WL_D1), 0, nullptr, scr, r, 32, c.lane); continue; } r -= I_D;
.LBB0_1238:
	s_andn2_b64 vcc, exec, s[6:7]
	s_cbranch_vccnz .LBB0_1240
	s_load_dwordx2 s[6:7], s[0:1], 0x30
	s_mul_i32 s5, s4, 0xb00000
	s_mul_hi_i32 s3, s4, 0xb00000
	s_mul_i32 s11, s4, 0x2900000
	s_mul_hi_i32 s10, s4, 0x2900000
	s_waitcnt lgkmcnt(0)
	s_add_u32 s8, s6, s5
	s_addc_u32 s9, s7, s3
	s_add_u32 s5, s78, s11
	s_mul_i32 s3, s4, 0xffffb0c0
	s_addc_u32 s6, s79, s10
	s_add_i32 s3, s31, s3
	s_and_b32 s7, s3, 0x1ffc0
	s_and_b32 s3, s27, 0x3e0
	v_or_b32_e32 v4, s3, v25
	v_or_b32_e32 v6, s7, v0
	v_lshlrev_b32_e32 v210, 2, v4
	v_lshl_add_u64 v[4:5], s[8:9], 0, v[210:211]
	v_lshlrev_b32_e32 v210, 12, v6
	v_lshl_add_u64 v[4:5], v[4:5], 0, v[210:211]
	s_movk_i32 s8, 0x2000
	v_add_co_u32_e32 v6, vcc, s8, v4
	s_movk_i32 s8, 0x4000
	s_nop 0
	v_addc_co_u32_e32 v7, vcc, 0, v5, vcc
	v_add_co_u32_e32 v8, vcc, s8, v4
	s_movk_i32 s8, 0x6000
	s_nop 0
	v_addc_co_u32_e32 v9, vcc, 0, v5, vcc
	v_add_co_u32_e32 v10, vcc, s8, v4
	s_mov_b32 s8, 0x8000
	s_nop 0
	v_addc_co_u32_e32 v11, vcc, 0, v5, vcc
	v_add_co_u32_e32 v12, vcc, s8, v4
	s_mov_b32 s8, 0xa000
	s_nop 0
	v_addc_co_u32_e32 v13, vcc, 0, v5, vcc
	v_add_co_u32_e32 v14, vcc, s8, v4
	s_mov_b32 s8, 0xc000
	s_nop 0
	v_addc_co_u32_e32 v15, vcc, 0, v5, vcc
	v_add_co_u32_e32 v16, vcc, s8, v4
	s_mov_b32 s8, 0xe000
	s_nop 0
	v_addc_co_u32_e32 v17, vcc, 0, v5, vcc
	v_add_co_u32_e32 v18, vcc, s8, v4
	s_mov_b32 s8, 0x12000
	s_nop 0
	v_addc_co_u32_e32 v19, vcc, 0, v5, vcc
	global_load_dword v22, v[4:5], off
	global_load_dword v23, v[6:7], off
	global_load_dword v63, v[8:9], off
	global_load_dword v64, v[10:11], off
	global_load_dword v65, v[12:13], off
	global_load_dword v66, v[14:15], off
	global_load_dword v67, v[16:17], off
	global_load_dword v68, v[18:19], off
	v_add_co_u32_e32 v6, vcc, s89, v4
	s_lshl_b32 s7, s7, 1
	s_nop 0
	v_addc_co_u32_e32 v7, vcc, 0, v5, vcc
	v_add_co_u32_e32 v8, vcc, s8, v4
	s_mov_b32 s8, 0x14000
	s_nop 0
	v_addc_co_u32_e32 v9, vcc, 0, v5, vcc
	v_add_co_u32_e32 v10, vcc, s8, v4
	s_mov_b32 s8, 0x18000
	s_nop 0
	v_addc_co_u32_e32 v11, vcc, 0, v5, vcc
	v_add_co_u32_e32 v12, vcc, s90, v4
	v_lshlrev_b32_e32 v210, 1, v2
	s_nop 0
	v_addc_co_u32_e32 v13, vcc, 0, v5, vcc
	v_add_co_u32_e32 v14, vcc, s8, v4
	s_mov_b32 s8, 0x1a000
	s_nop 0
	v_addc_co_u32_e32 v15, vcc, 0, v5, vcc
	v_add_co_u32_e32 v16, vcc, s8, v4
	s_mov_b32 s8, 0x1c000
	s_nop 0
	v_addc_co_u32_e32 v17, vcc, 0, v5, vcc
	v_add_co_u32_e32 v18, vcc, s8, v4
	s_mov_b32 s8, 0x1e000
	s_nop 0
	v_addc_co_u32_e32 v19, vcc, 0, v5, vcc
	v_add_co_u32_e32 v20, vcc, s8, v4
	s_mov_b32 s8, 0x20000
	s_nop 0
	v_addc_co_u32_e32 v21, vcc, 0, v5, vcc
	global_load_dword v69, v[6:7], off
	global_load_dword v70, v[8:9], off
	global_load_dword v71, v[10:11], off
	global_load_dword v72, v[12:13], off
	global_load_dword v73, v[14:15], off
	global_load_dword v74, v[16:17], off
	global_load_dword v75, v[18:19], off
	global_load_dword v76, v[20:21], off
	v_add_co_u32_e32 v6, vcc, s8, v4
	s_mov_b32 s8, 0x22000
	s_nop 0
	v_addc_co_u32_e32 v7, vcc, 0, v5, vcc
	v_add_co_u32_e32 v8, vcc, s8, v4
	s_mov_b32 s8, 0x24000
	s_nop 0
	v_addc_co_u32_e32 v9, vcc, 0, v5, vcc
	v_add_co_u32_e32 v10, vcc, s8, v4
	s_mov_b32 s8, 0x26000
	s_nop 0
	v_addc_co_u32_e32 v11, vcc, 0, v5, vcc
	v_add_co_u32_e32 v12, vcc, s8, v4
	s_mov_b32 s8, 0x28000
	s_nop 0
	v_addc_co_u32_e32 v13, vcc, 0, v5, vcc
	v_add_co_u32_e32 v14, vcc, s8, v4
	s_mov_b32 s8, 0x2a000
	s_nop 0
	v_addc_co_u32_e32 v15, vcc, 0, v5, vcc
	v_add_co_u32_e32 v16, vcc, s8, v4
	s_mov_b32 s8, 0x2c000
	s_nop 0
	v_addc_co_u32_e32 v17, vcc, 0, v5, vcc
	v_add_co_u32_e32 v18, vcc, s8, v4
	s_mov_b32 s8, 0x2e000
	s_nop 0
	v_addc_co_u32_e32 v19, vcc, 0, v5, vcc
	v_add_co_u32_e32 v20, vcc, s8, v4
	s_mov_b32 s8, 0x30000
	s_nop 0
	v_addc_co_u32_e32 v21, vcc, 0, v5, vcc
	global_load_dword v77, v[6:7], off
	global_load_dword v78, v[8:9], off
	global_load_dword v79, v[10:11], off
	global_load_dword v80, v[12:13], off
	global_load_dword v81, v[14:15], off
	global_load_dword v82, v[16:17], off
	global_load_dword v83, v[18:19], off
	s_nop 0
	global_load_dword v20, v[20:21], off
	v_add_co_u32_e32 v6, vcc, s8, v4
	s_mov_b32 s8, 0x32000
	s_nop 0
	v_addc_co_u32_e32 v7, vcc, 0, v5, vcc
	v_add_co_u32_e32 v8, vcc, s8, v4
	s_mov_b32 s8, 0x34000
	s_nop 0
	v_addc_co_u32_e32 v9, vcc, 0, v5, vcc
	v_add_co_u32_e32 v10, vcc, s8, v4
	s_mov_b32 s8, 0x36000
	s_nop 0
	v_addc_co_u32_e32 v11, vcc, 0, v5, vcc
	v_add_co_u32_e32 v12, vcc, s8, v4
	s_mov_b32 s8, 0x38000
	s_nop 0
	v_addc_co_u32_e32 v13, vcc, 0, v5, vcc
	v_add_co_u32_e32 v14, vcc, s8, v4
	s_mov_b32 s8, 0x3a000
	s_nop 0
	v_addc_co_u32_e32 v15, vcc, 0, v5, vcc
	v_add_co_u32_e32 v16, vcc, s8, v4
	s_mov_b32 s8, 0x3c000
	s_nop 0
	v_addc_co_u32_e32 v17, vcc, 0, v5, vcc
	v_add_co_u32_e32 v18, vcc, s8, v4
	s_mov_b32 s8, 0x3e000
	s_nop 0
	v_addc_co_u32_e32 v19, vcc, 0, v5, vcc
	v_add_co_u32_e32 v4, vcc, s8, v4
	s_add_u32 s8, s5, s7
	s_nop 0
	v_addc_co_u32_e32 v5, vcc, 0, v5, vcc
	global_load_dword v6, v[6:7], off
	s_nop 0
	global_load_dword v7, v[8:9], off
	s_nop 0
	global_load_dword v8, v[10:11], off
	global_load_dword v9, v[12:13], off
	s_nop 0
	global_load_dword v10, v[14:15], off
	global_load_dword v11, v[16:17], off
	global_load_dword v12, v[18:19], off
	s_nop 0
	global_load_dword v4, v[4:5], off
	v_add_u32_e32 v5, 0x400, v26
	s_waitcnt vmcnt(30)
; __device__ __forceinline__ unsigned cvtpk(float lo, float hi) { f32x2_t v = {lo, hi}; bf16x2_t b = __builtin_convertvector(v, bf16x2_t); return __builtin_bit_cast(unsigned, b); }
; __device__ __forceinline__ void transpose_item(const float* W, int K, int N, bf16_t* WT, int mode, const float* kscale, float* scr, int item, int nblk, int lane) {
;     ...
;     for (int i = 0; i < 32; ++i) { const int kk = 2 * i + (lane >> 5); float v = wv[i]; if (kscale) v *= kscale[k0 + kk]; scr[kk * 33 + (lane & 31)] = v; }
;     __builtin_amdgcn_s_waitcnt(0); asm volatile("" ::: "memory");
;     const int c = lane & 7;
;     int drow0 = n0; if (mode == 1) drow0 = (n0 / 128) * 256 + (n0 % 128); else if (mode == 2) drow0 = (n0 / 128) * 256 + 128 + (n0 % 128);
; #pragma unroll
;     for (int j = 0; j < 4; ++j) { const int n = (lane >> 3) + 8 * j; const float* s = scr + (8 * c) * 33 + n;
;         u32x4 o; o.x = cvtpk(s[0 * 33], s[1 * 33]); o.y = cvtpk(s[2 * 33], s[3 * 33]); o.z = cvtpk(s[4 * 33], s[5 * 33]); o.w = cvtpk(s[6 * 33], s[7 * 33]);
;         *(u32x4*)(WT + (size_t)(drow0 + n) * K + k0 + 8 * c) = o; }
;     __builtin_amdgcn_s_waitcnt(0); asm volatile("" ::: "memory");
	ds_write2_b32 v26, v22, v23 offset1:66
	s_waitcnt vmcnt(28)
	ds_write2_b32 v26, v63, v64 offset0:132 offset1:198
	s_waitcnt vmcnt(26)
	ds_write2_b32 v5, v65, v66 offset0:8 offset1:74
	s_waitcnt vmcnt(24)
	ds_write2_b32 v5, v67, v68 offset0:140 offset1:206
	v_add_u32_e32 v5, 0x800, v26
	s_waitcnt vmcnt(22)
	ds_write2_b32 v5, v69, v70 offset0:16 offset1:82
	s_waitcnt vmcnt(20)
	ds_write2_b32 v5, v71, v72 offset0:148 offset1:214
	v_add_u32_e32 v5, 0xc00, v26
	s_waitcnt vmcnt(18)
	ds_write2_b32 v5, v73, v74 offset0:24 offset1:90
	s_waitcnt vmcnt(16)
	ds_write2_b32 v5, v75, v76 offset0:156 offset1:222
	v_add_u32_e32 v5, 0x1000, v26
	s_waitcnt vmcnt(14)
	ds_write2_b32 v5, v77, v78 offset0:32 offset1:98
	s_waitcnt vmcnt(12)
	ds_write2_b32 v5, v79, v80 offset0:164 offset1:230
	v_add_u32_e32 v5, 0x1400, v26
	s_waitcnt vmcnt(10)
	ds_write2_b32 v5, v81, v82 offset0:40 offset1:106
	s_waitcnt vmcnt(8)
	ds_write2_b32 v5, v83, v20 offset0:172 offset1:238
	v_add_u32_e32 v5, 0x1800, v26
	s_waitcnt vmcnt(6)
	ds_write2_b32 v5, v6, v7 offset0:48 offset1:114
	s_waitcnt vmcnt(4)
	ds_write2_b32 v5, v8, v9 offset0:180 offset1:246
	v_add_u32_e32 v5, 0x1c00, v26
	s_waitcnt vmcnt(2)
	ds_write2_b32 v5, v10, v11 offset0:56 offset1:122
	s_waitcnt vmcnt(0)
	ds_write2_b32 v5, v12, v4 offset0:188 offset1:254
	s_waitcnt vmcnt(0) expcnt(0) lgkmcnt(0)
	s_addc_u32 s9, s6, 0
	ds_read2_b32 v[8:9], v28 offset0:33 offset1:41
	ds_read2_b32 v[10:11], v28 offset1:8
	ds_read2_b32 v[12:13], v28 offset0:66 offset1:74
	ds_read2_b32 v[14:15], v28 offset0:99 offset1:107
	ds_read2_b32 v[16:17], v28 offset0:132 offset1:140
	ds_read2_b32 v[18:19], v28 offset0:165 offset1:173
	ds_read2_b32 v[20:21], v28 offset0:198 offset1:206
	ds_read2_b32 v[22:23], v28 offset0:231 offset1:239
	v_lshl_add_u64 v[4:5], s[8:9], 0, v[210:211]
	s_mov_b64 s[6:7], 0xc00000
	v_lshl_add_u64 v[64:65], v[4:5], 0, s[6:7]
	s_waitcnt lgkmcnt(6)
	v_cvt_pk_bf16_f32 v4, v10, v8
	v_or_b32_e32 v8, s3, v27
	v_mul_u32_u24_e32 v8, 0xb00, v8
	v_lshlrev_b32_e32 v210, 1, v8
	s_waitcnt lgkmcnt(4)
	v_cvt_pk_bf16_f32 v5, v12, v14
	s_waitcnt lgkmcnt(2)
	v_cvt_pk_bf16_f32 v6, v16, v18
	s_waitcnt lgkmcnt(0)
	v_cvt_pk_bf16_f32 v7, v20, v22
	v_lshl_add_u64 v[66:67], v[64:65], 0, v[210:211]
	v_or_b32_e32 v8, s3, v29
	global_store_dwordx4 v[66:67], v[4:7], off
	v_mul_u32_u24_e32 v8, 0xb00, v8
	v_lshlrev_b32_e32 v210, 1, v8
	v_cvt_pk_bf16_f32 v4, v11, v9
	v_cvt_pk_bf16_f32 v5, v13, v15
	v_cvt_pk_bf16_f32 v6, v17, v19
	v_cvt_pk_bf16_f32 v7, v21, v23
	ds_read2_b32 v[10:11], v28 offset0:16 offset1:24
	ds_read2_b32 v[12:13], v28 offset0:49 offset1:57
	ds_read2_b32 v[14:15], v28 offset0:82 offset1:90
	ds_read2_b32 v[16:17], v28 offset0:115 offset1:123
	ds_read2_b32 v[18:19], v28 offset0:148 offset1:156
	ds_read2_b32 v[20:21], v28 offset0:181 offset1:189
	ds_read2_b32 v[22:23], v28 offset0:214 offset1:222
	ds_read2_b32 v[66:67], v28 offset0:247 offset1:255
	v_lshl_add_u64 v[8:9], v[64:65], 0, v[210:211]
	global_store_dwordx4 v[8:9], v[4:7], off
	v_or_b32_e32 v8, s3, v30
	v_mul_u32_u24_e32 v8, 0xb00, v8
	v_lshlrev_b32_e32 v210, 1, v8
	s_waitcnt lgkmcnt(6)
	v_cvt_pk_bf16_f32 v4, v10, v12
	s_waitcnt lgkmcnt(4)
	v_cvt_pk_bf16_f32 v5, v14, v16
	s_waitcnt lgkmcnt(2)
	v_cvt_pk_bf16_f32 v6, v18, v20
	s_waitcnt lgkmcnt(0)
	v_cvt_pk_bf16_f32 v7, v22, v66
	v_lshl_add_u64 v[8:9], v[64:65], 0, v[210:211]
	global_store_dwordx4 v[8:9], v[4:7], off
	v_or_b32_e32 v8, s3, v31
	v_mul_u32_u24_e32 v8, 0xb00, v8
	v_lshlrev_b32_e32 v210, 1, v8
	v_cvt_pk_bf16_f32 v4, v11, v13
	v_cvt_pk_bf16_f32 v5, v15, v17
	v_cvt_pk_bf16_f32 v6, v19, v21
	v_cvt_pk_bf16_f32 v7, v23, v67
	v_lshl_add_u64 v[8:9], v[64:65], 0, v[210:211]
	global_store_dwordx4 v[8:9], v[4:7], off
	s_waitcnt lgkmcnt(0)

; __device__ __forceinline__ unsigned cvtpk(float lo, float hi) { f32x2_t v = {lo, hi}; bf16x2_t b = __builtin_convertvector(v, bf16x2_t); return __builtin_bit_cast(unsigned, b); }
; __device__ __forceinline__ void transpose_item(const float* W, int K, int N, bf16_t* WT, int mode, const float* kscale, float* scr, int item, int nblk, int lane) {
;     ...
;     for (int i = 0; i < 32; ++i) { const int kk = 2 * i + (lane >> 5); float v = wv[i]; if (kscale) v *= kscale[k0 + kk]; scr[kk * 33 + (lane & 31)] = v; }
;     __builtin_amdgcn_s_waitcnt(0); asm volatile("" ::: "memory");
;     const int c = lane & 7;
;     int drow0 = n0; if (mode == 1) drow0 = (n0 / 128) * 256 + (n0 % 128); else if (mode == 2) drow0 = (n0 / 128) * 256 + 128 + (n0 % 128);
; #pragma unroll
;     for (int j = 0; j < 4; ++j) { const int n = (lane >> 3) + 8 * j; const float* s = scr + (8 * c) * 33 + n;
;         u32x4 o; o.x = cvtpk(s[0 * 33], s[1 * 33]); o.y = cvtpk(s[2 * 33], s[3 * 33]); o.z = cvtpk(s[4 * 33], s[5 * 33]); o.w = cvtpk(s[6 * 33], s[7 * 33]);
;         *(u32x4*)(WT + (size_t)(drow0 + n) * K + k0 + 8 * c) = o; }
;     __builtin_amdgcn_s_waitcnt(0); asm volatile("" ::: "memory");
.LBB0_1266:
	s_mul_i32 s7, s4, 0x2900000
	s_mul_hi_i32 s6, s4, 0x2900000
	s_add_u32 s7, s16, s7
	s_addc_u32 s9, s25, s6
	s_lshl_b32 s5, s5, 6
	s_and_b32 s5, s5, 0x1f00
	s_and_b32 s6, s8, 0x60
	ds_write_b32 v61, v6
	ds_write_b32 v62, v7
	s_waitcnt vmcnt(0) expcnt(0) lgkmcnt(0)
	s_or_b32 s5, s6, s5
	s_bitset1_b32 s5, 7
	ds_read2_b32 v[8:9], v28 offset0:33 offset1:41
	ds_read2_b32 v[10:11], v28 offset1:8
	ds_read2_b32 v[12:13], v28 offset0:66 offset1:74
	ds_read2_b32 v[14:15], v28 offset0:99 offset1:107
	ds_read2_b32 v[16:17], v28 offset0:132 offset1:140
	ds_read2_b32 v[18:19], v28 offset0:165 offset1:173
	ds_read2_b32 v[20:21], v28 offset0:198 offset1:206
	ds_read2_b32 v[22:23], v28 offset0:231 offset1:239
	s_and_b32 s5, s5, 0x1fe0
	s_lshl_b32 s3, s3, 1
	s_add_u32 s6, s7, s3
	s_addc_u32 s7, s9, 0
	v_lshlrev_b32_e32 v210, 1, v2
	s_waitcnt lgkmcnt(6)
	v_cvt_pk_bf16_f32 v4, v10, v8
	v_or_b32_e32 v8, s5, v27
	v_lshl_add_u64 v[64:65], s[6:7], 0, v[210:211]
	v_lshlrev_b32_e32 v210, 11, v8
	s_waitcnt lgkmcnt(4)
	v_cvt_pk_bf16_f32 v5, v12, v14
	s_waitcnt lgkmcnt(2)
	v_cvt_pk_bf16_f32 v6, v16, v18
	s_waitcnt lgkmcnt(0)
	v_cvt_pk_bf16_f32 v7, v20, v22
	v_lshl_add_u64 v[66:67], v[64:65], 0, v[210:211]
	global_store_dwordx4 v[66:67], v[4:7], off
	v_or_b32_e32 v8, s5, v29
	v_lshlrev_b32_e32 v210, 11, v8
	v_cvt_pk_bf16_f32 v4, v11, v9
	v_cvt_pk_bf16_f32 v5, v13, v15
	v_cvt_pk_bf16_f32 v6, v17, v19
	v_cvt_pk_bf16_f32 v7, v21, v23
	ds_read2_b32 v[10:11], v28 offset0:49 offset1:57
	ds_read2_b32 v[12:13], v28 offset0:16 offset1:24
	ds_read2_b32 v[14:15], v28 offset0:82 offset1:90
	ds_read2_b32 v[16:17], v28 offset0:115 offset1:123
	ds_read2_b32 v[18:19], v28 offset0:148 offset1:156
	ds_read2_b32 v[20:21], v28 offset0:181 offset1:189
	ds_read2_b32 v[22:23], v28 offset0:214 offset1:222
	ds_read2_b32 v[66:67], v28 offset0:247 offset1:255
	v_lshl_add_u64 v[8:9], v[64:65], 0, v[210:211]
	global_store_dwordx4 v[8:9], v[4:7], off
	v_or_b32_e32 v8, s5, v30
	v_lshlrev_b32_e32 v210, 11, v8
	s_waitcnt lgkmcnt(6)
	v_cvt_pk_bf16_f32 v4, v12, v10
	s_waitcnt lgkmcnt(4)
	v_cvt_pk_bf16_f32 v5, v14, v16
	s_waitcnt lgkmcnt(2)
	v_cvt_pk_bf16_f32 v6, v18, v20
	s_waitcnt lgkmcnt(0)
	v_cvt_pk_bf16_f32 v7, v22, v66
	v_lshl_add_u64 v[8:9], v[64:65], 0, v[210:211]
	global_store_dwordx4 v[8:9], v[4:7], off
	v_or_b32_e32 v8, s5, v31
	v_lshlrev_b32_e32 v210, 11, v8
	v_cvt_pk_bf16_f32 v4, v13, v11
	v_cvt_pk_bf16_f32 v5, v15, v17
	v_cvt_pk_bf16_f32 v6, v19, v21
	v_cvt_pk_bf16_f32 v7, v23, v67
	v_lshl_add_u64 v[8:9], v[64:65], 0, v[210:211]
	global_store_dwordx4 v[8:9], v[4:7], off
	s_waitcnt lgkmcnt(0)
